# residual epilogues: 8 exec-masked 64-byte PART stores per wave replaced by 2 full-wave 256-byte stores (row sums parked in spare VGPRs, lane (fr,fq) stores group fq)
# speedup vs baseline: 1.0040x; 1.0040x over previous
; #define PG8_LAS __attribute__((address_space(3)))
;     __device__ __forceinline__ void operator()(const f32x4 (&acc)[2][2][4][2], const Unit& u, int wr, int wc, int fr, int fq, PG8_LAS unsigned char* stg) const {
;         const int lane = fq * 16 + fr;
;         const size_t colw = (size_t)u.pn * BM + wc * 64;
;         const int rowb = u.pm * BM + wr * 64;
;         PG8_LAS unsigned char* st = stg + fr * 144 + fq * 16;
; #pragma unroll
;         for (int ai = 0; ai < 2; ++ai) {
;         asm volatile("" ::: "memory");
;         u32x4 xin[4][2];
; #pragma unroll
;         for (int m = 0; m < 4; ++m)
; #pragma unroll
;             for (int i = 0; i < 2; ++i) { const int c = lane + 64 * i; xin[m][i] = *(const u32x4*)(xb + (size_t)(rowb + ai * HALF + m * 16 + (c >> 3)) * 1024 + colw + (c & 7) * 8); }
; #pragma unroll
;         for (int m = 0; m < 4; ++m) {
;             const int row = rowb + ai * HALF + m * 16 + fr;
; #pragma unroll
;             for (int i = 0; i < 2; ++i) { const int c = lane + 64 * i; *(PG8_LAS u32x4*)(stg + (c >> 3) * 144 + (c & 7) * 16) = xin[m][i]; }
;             float ss = 0.f;
; #pragma unroll
;             for (int bj = 0; bj < 2; ++bj) {
;                 const u32x4 xo = *(const PG8_LAS u32x4*)(st + bj * 64);
;                 float v[8];
; #pragma unroll
;                 for (int i = 0; i < 4; ++i) { v[2 * i] = __uint_as_float(xo[i] << 16) + acc[ai][bj][m][i >> 1][(2 * i) & 3]; v[2 * i + 1] = __uint_as_float(xo[i] & 0xffff0000u) + acc[ai][bj][m][i >> 1][(2 * i + 1) & 3]; }
;                 u32x4 w; w.x = cvt_pk_bf16(v[0], v[1]); w.y = cvt_pk_bf16(v[2], v[3]); w.z = cvt_pk_bf16(v[4], v[5]); w.w = cvt_pk_bf16(v[6], v[7]);
;                 *(PG8_LAS u32x4*)(st + bj * 64) = w;
;                 ss += ((v[0] * v[0] + v[1] * v[1]) + (v[2] * v[2] + v[3] * v[3])) + ((v[4] * v[4] + v[5] * v[5]) + (v[6] * v[6] + v[7] * v[7]));
;             }
; #pragma unroll
;             for (int i = 0; i < 2; ++i) { const int c = lane + 64 * i; const u32x4 w = *(const PG8_LAS u32x4*)(stg + (c >> 3) * 144 + (c & 7) * 16);
;                 *(u32x4*)(xo_ + (size_t)(row - fr + (c >> 3)) * 1024 + colw + (c & 7) * 8) = w; }
;             ss = sum_x16(ss); ss = sum_x32(ss);
;             if (fq == 0) po_[(size_t)(u.pn * 4 + wc) * 65536 + row] = ss;
.LBB0_756:
	s_ashr_i32 s47, s46, 31
	s_lshl_b64 s[44:45], s[46:47], 8
	s_lshl_b32 s29, s50, 8
	s_or_b64 s[48:49], s[44:45], s[22:23]
	s_add_i32 s44, s29, s15
	v_or_b32_e32 v130, s44, v206
	s_lshl_b64 s[48:49], s[48:49], 1
	v_ashrrev_i32_e32 v131, 31, v130
	v_lshl_add_u64 v[182:183], v[176:177], 0, s[48:49]
	v_lshlrev_b64 v[198:199], 11, v[130:131]
	v_lshl_add_u64 v[130:131], v[182:183], 0, v[198:199]
	global_load_dwordx4 v[154:157], v[130:131], off
	v_or_b32_e32 v130, s44, v207
	v_ashrrev_i32_e32 v131, 31, v130
	v_lshlrev_b64 v[196:197], 11, v[130:131]
	v_lshl_add_u64 v[130:131], v[182:183], 0, v[196:197]
	global_load_dwordx4 v[160:163], v[130:131], off
	s_lshl_b32 s29, s46, 2
	s_or_b32 s46, s29, s13
	s_or_b32 s29, s44, 16
	v_or_b32_e32 v130, s29, v206
	v_ashrrev_i32_e32 v131, 31, v130
	v_lshlrev_b64 v[194:195], 11, v[130:131]
	v_lshl_add_u64 v[130:131], v[182:183], 0, v[194:195]
	global_load_dwordx4 v[146:149], v[130:131], off
	v_or_b32_e32 v130, s29, v207
	v_ashrrev_i32_e32 v131, 31, v130
	v_lshlrev_b64 v[192:193], 11, v[130:131]
	v_lshl_add_u64 v[130:131], v[182:183], 0, v[192:193]
	s_or_b32 s29, s44, 32
	global_load_dwordx4 v[150:153], v[130:131], off
	v_or_b32_e32 v130, s29, v206
	v_ashrrev_i32_e32 v131, 31, v130
	v_lshlrev_b64 v[188:189], 11, v[130:131]
	v_lshl_add_u64 v[130:131], v[182:183], 0, v[188:189]
	global_load_dwordx4 v[134:137], v[130:131], off
	v_or_b32_e32 v130, s29, v207
	v_ashrrev_i32_e32 v131, 31, v130
	v_lshlrev_b64 v[186:187], 11, v[130:131]
	v_lshl_add_u64 v[130:131], v[182:183], 0, v[186:187]
	s_or_b32 s29, s44, 48
	global_load_dwordx4 v[138:141], v[130:131], off
	v_or_b32_e32 v130, s29, v206
	v_or_b32_e32 v142, s29, v207
	v_ashrrev_i32_e32 v131, 31, v130
	v_ashrrev_i32_e32 v143, 31, v142
	v_lshlrev_b64 v[184:185], 11, v[130:131]
	v_lshlrev_b64 v[190:191], 11, v[142:143]
	v_lshl_add_u64 v[130:131], v[182:183], 0, v[184:185]
	v_lshl_add_u64 v[142:143], v[182:183], 0, v[190:191]
	global_load_dwordx4 v[130:133], v[130:131], off
	s_ashr_i32 s47, s46, 31
	global_load_dwordx4 v[142:145], v[142:143], off
	s_lshl_b64 s[46:47], s[46:47], 18
	s_waitcnt vmcnt(0)
	ds_write_b128 v209, v[154:157]
	ds_write_b128 v209, v[160:163] offset:1152
	ds_read_b128 v[154:157], v210
	s_waitcnt lgkmcnt(0)
	v_lshlrev_b32_e32 v160, 16, v154
	v_and_b32_e32 v154, 0xffff0000, v154
	v_add_f32_e32 v127, v127, v154
	v_lshlrev_b32_e32 v154, 16, v155
	v_add_f32_e32 v128, v128, v154
	v_and_b32_e32 v154, 0xffff0000, v155
	v_add_f32_e32 v129, v129, v154
	v_lshlrev_b32_e32 v154, 16, v156
	v_add_f32_e32 v154, v122, v154
	v_and_b32_e32 v122, 0xffff0000, v156
	v_add_f32_e32 v155, v123, v122
	v_lshlrev_b32_e32 v122, 16, v157
	v_add_f32_e32 v156, v124, v122
	v_and_b32_e32 v122, 0xffff0000, v157
	v_add_f32_e32 v126, v126, v160
	v_add_f32_e32 v157, v125, v122
	v_cvt_pk_bf16_f32 v122, v126, v127
	v_cvt_pk_bf16_f32 v123, v128, v129
	v_cvt_pk_bf16_f32 v124, v154, v155
	v_cvt_pk_bf16_f32 v125, v156, v157
	ds_write_b128 v210, v[122:125]
	v_mul_f32_e32 v122, v127, v127
	v_mul_f32_e32 v123, v129, v129
	v_fmac_f32_e32 v122, v126, v126
	v_fmac_f32_e32 v123, v128, v128
	v_add_f32_e32 v122, v122, v123
	v_mul_f32_e32 v123, v155, v155
	v_mul_f32_e32 v124, v157, v157
	v_fmac_f32_e32 v123, v154, v154
	v_fmac_f32_e32 v124, v156, v156
	v_add_f32_e32 v123, v123, v124
	v_add_f32_e32 v126, v122, v123
	ds_read_b128 v[122:125], v210 offset:64
	s_waitcnt lgkmcnt(0)
	v_lshlrev_b32_e32 v127, 16, v122
	v_and_b32_e32 v122, 0xffff0000, v122
	v_add_f32_e32 v119, v119, v122
	v_lshlrev_b32_e32 v122, 16, v123
	v_add_f32_e32 v120, v120, v122
	v_and_b32_e32 v122, 0xffff0000, v123
	v_add_f32_e32 v121, v121, v122
	v_lshlrev_b32_e32 v122, 16, v124
	v_add_f32_e32 v122, v114, v122
	v_and_b32_e32 v114, 0xffff0000, v124
	v_add_f32_e32 v123, v115, v114
	v_lshlrev_b32_e32 v114, 16, v125
	v_add_f32_e32 v124, v116, v114
	v_and_b32_e32 v114, 0xffff0000, v125
	v_add_f32_e32 v118, v118, v127
	v_add_f32_e32 v125, v117, v114
	v_cvt_pk_bf16_f32 v114, v118, v119
	v_cvt_pk_bf16_f32 v115, v120, v121
	v_cvt_pk_bf16_f32 v116, v122, v123
	v_cvt_pk_bf16_f32 v117, v124, v125
	ds_write_b128 v210, v[114:117] offset:64
	v_mul_f32_e32 v114, v119, v119
	v_mul_f32_e32 v115, v121, v121
	v_fmac_f32_e32 v114, v118, v118
	v_fmac_f32_e32 v115, v120, v120
	v_add_f32_e32 v114, v114, v115
	v_mul_f32_e32 v115, v123, v123
	v_mul_f32_e32 v116, v125, v125
	v_fmac_f32_e32 v115, v122, v122
	v_fmac_f32_e32 v116, v124, v124
	v_add_f32_e32 v115, v115, v116
	v_add_f32_e32 v114, v114, v115
	v_add_f32_e32 v120, v126, v114
	ds_read_b128 v[114:117], v211
	v_lshl_add_u64 v[118:119], s[76:77], 0, v[198:199]
	v_lshl_add_u64 v[118:119], v[118:119], 0, s[48:49]
	v_lshl_add_u64 v[118:119], v[118:119], 0, v[0:1]
	s_waitcnt lgkmcnt(0)
	global_store_dwordx4 v[118:119], v[114:117], off nt
	ds_read_b128 v[114:117], v211 offset:1152
	v_lshl_add_u64 v[118:119], s[76:77], 0, v[196:197]
	v_lshl_add_u64 v[118:119], v[118:119], 0, s[48:49]
	v_lshl_add_u64 v[118:119], v[118:119], 0, v[0:1]
	s_waitcnt lgkmcnt(0)
	global_store_dwordx4 v[118:119], v[114:117], off nt
	s_nop 1
	v_mov_b32_e32 v114, v120
	s_nop 1
	v_permlane16_swap_b32_e32 v120, v114
	v_add_f32_e32 v114, v120, v114
	v_mov_b32_e32 v115, v114
	s_nop 1
	v_permlane32_swap_b32_e32 v114, v115
	v_add_f32_e32 v164, v114, v115
	ds_write_b128 v209, v[146:149]
	ds_write_b128 v209, v[150:153] offset:1152
	ds_read_b128 v[114:117], v210
	s_waitcnt lgkmcnt(0)
; #define PG8_LAS __attribute__((address_space(3)))
; __device__ __forceinline__ unsigned cvt_pk_bf16(float lo, float hi) { unsigned r; asm volatile("v_cvt_pk_bf16_f32 %0, %1, %2" : "=v"(r) : "v"(lo), "v"(hi)); return r; }
; __device__ __forceinline__ float sum_x16(float s) { auto r = __builtin_amdgcn_permlane16_swap(__float_as_uint(s), __float_as_uint(s), false, false); return __uint_as_float(r[0]) + __uint_as_float(r[1]); }
; __device__ __forceinline__ float sum_x32(float s) { auto r = __builtin_amdgcn_permlane32_swap(__float_as_uint(s), __float_as_uint(s), false, false); return __uint_as_float(r[0]) + __uint_as_float(r[1]); }
;     __device__ __forceinline__ void operator()(const f32x4 (&acc)[2][2][4][2], const Unit& u, int wr, int wc, int fr, int fq, PG8_LAS unsigned char* stg) const {
;     ...
;         for (int m = 0; m < 4; ++m) {
;             const int row = rowb + ai * HALF + m * 16 + fr;
; #pragma unroll
;             for (int i = 0; i < 2; ++i) { const int c = lane + 64 * i; *(PG8_LAS u32x4*)(stg + (c >> 3) * 144 + (c & 7) * 16) = xin[m][i]; }
;             float ss = 0.f;
; #pragma unroll
;             for (int bj = 0; bj < 2; ++bj) {
;                 const u32x4 xo = *(const PG8_LAS u32x4*)(st + bj * 64);
;                 float v[8];
; #pragma unroll
;                 for (int i = 0; i < 4; ++i) { v[2 * i] = __uint_as_float(xo[i] << 16) + acc[ai][bj][m][i >> 1][(2 * i) & 3]; v[2 * i + 1] = __uint_as_float(xo[i] & 0xffff0000u) + acc[ai][bj][m][i >> 1][(2 * i + 1) & 3]; }
;                 u32x4 w; w.x = cvt_pk_bf16(v[0], v[1]); w.y = cvt_pk_bf16(v[2], v[3]); w.z = cvt_pk_bf16(v[4], v[5]); w.w = cvt_pk_bf16(v[6], v[7]);
;                 *(PG8_LAS u32x4*)(st + bj * 64) = w;
;                 ss += ((v[0] * v[0] + v[1] * v[1]) + (v[2] * v[2] + v[3] * v[3])) + ((v[4] * v[4] + v[5] * v[5]) + (v[6] * v[6] + v[7] * v[7]));
;             }
; #pragma unroll
;             for (int i = 0; i < 2; ++i) { const int c = lane + 64 * i; const u32x4 w = *(const PG8_LAS u32x4*)(stg + (c >> 3) * 144 + (c & 7) * 16);
;                 *(u32x4*)(xo_ + (size_t)(row - fr + (c >> 3)) * 1024 + colw + (c & 7) * 8) = w; }
;             ss = sum_x16(ss); ss = sum_x32(ss);
;             if (fq == 0) po_[(size_t)(u.pn * 4 + wc) * 65536 + row] = ss;
	v_lshlrev_b32_e32 v118, 16, v114
	v_and_b32_e32 v114, 0xffff0000, v114
	v_add_f32_e32 v111, v111, v114
	v_and_b32_e32 v114, 0xffff0000, v115
	v_add_f32_e32 v113, v113, v114
	v_lshlrev_b32_e32 v114, 16, v116
	v_add_f32_e32 v114, v106, v114
	v_and_b32_e32 v106, 0xffff0000, v116
	v_lshlrev_b32_e32 v119, 16, v115
	v_add_f32_e32 v115, v107, v106
	v_lshlrev_b32_e32 v106, 16, v117
	v_add_f32_e32 v116, v108, v106
	v_and_b32_e32 v106, 0xffff0000, v117
	v_add_f32_e32 v110, v110, v118
	v_add_f32_e32 v112, v112, v119
	v_add_f32_e32 v117, v109, v106
	v_cvt_pk_bf16_f32 v106, v110, v111
	v_cvt_pk_bf16_f32 v107, v112, v113
	v_cvt_pk_bf16_f32 v108, v114, v115
	v_cvt_pk_bf16_f32 v109, v116, v117
	ds_write_b128 v210, v[106:109]
	v_mul_f32_e32 v106, v111, v111
	v_mul_f32_e32 v107, v113, v113
	v_fmac_f32_e32 v106, v110, v110
	v_fmac_f32_e32 v107, v112, v112
	v_add_f32_e32 v110, v106, v107
	ds_read_b128 v[106:109], v210 offset:64
	v_mul_f32_e32 v111, v115, v115
	v_mul_f32_e32 v112, v117, v117
	v_fmac_f32_e32 v111, v114, v114
	v_fmac_f32_e32 v112, v116, v116
	v_add_f32_e32 v111, v111, v112
	v_add_f32_e32 v110, v110, v111
	s_waitcnt lgkmcnt(0)
	v_lshlrev_b32_e32 v111, 16, v106
	v_and_b32_e32 v106, 0xffff0000, v106
	v_add_f32_e32 v103, v103, v106
	v_lshlrev_b32_e32 v106, 16, v107
	v_add_f32_e32 v104, v104, v106
	v_and_b32_e32 v106, 0xffff0000, v107
	v_add_f32_e32 v105, v105, v106
	v_lshlrev_b32_e32 v106, 16, v108
	v_add_f32_e32 v106, v98, v106
	v_and_b32_e32 v98, 0xffff0000, v108
	v_add_f32_e32 v107, v99, v98
	v_lshlrev_b32_e32 v98, 16, v109
	v_add_f32_e32 v108, v100, v98
	v_and_b32_e32 v98, 0xffff0000, v109
	v_add_f32_e32 v102, v102, v111
	v_add_f32_e32 v109, v101, v98
	v_cvt_pk_bf16_f32 v98, v102, v103
	v_cvt_pk_bf16_f32 v99, v104, v105
	v_cvt_pk_bf16_f32 v100, v106, v107
	v_cvt_pk_bf16_f32 v101, v108, v109
	ds_write_b128 v210, v[98:101] offset:64
	v_mul_f32_e32 v98, v103, v103
	v_mul_f32_e32 v99, v105, v105
	v_fmac_f32_e32 v98, v102, v102
	v_fmac_f32_e32 v99, v104, v104
	v_add_f32_e32 v98, v98, v99
	v_mul_f32_e32 v99, v107, v107
	v_mul_f32_e32 v100, v109, v109
	v_fmac_f32_e32 v99, v106, v106
	v_fmac_f32_e32 v100, v108, v108
	v_add_f32_e32 v99, v99, v100
	v_add_f32_e32 v98, v98, v99
	v_add_f32_e32 v108, v110, v98
	ds_read_b128 v[98:101], v211
	v_lshl_add_u64 v[102:103], s[76:77], 0, v[194:195]
	v_lshl_add_u64 v[102:103], v[102:103], 0, s[48:49]
	v_lshl_add_u64 v[106:107], v[102:103], 0, v[0:1]
	ds_read_b128 v[102:105], v211 offset:1152
	s_waitcnt lgkmcnt(1)
	global_store_dwordx4 v[106:107], v[98:101], off nt
	s_nop 1
	v_lshl_add_u64 v[98:99], s[76:77], 0, v[192:193]
	v_lshl_add_u64 v[98:99], v[98:99], 0, s[48:49]
	v_lshl_add_u64 v[98:99], v[98:99], 0, v[0:1]
	s_waitcnt lgkmcnt(0)
	global_store_dwordx4 v[98:99], v[102:105], off nt
	v_mov_b32_e32 v98, v108
	s_nop 1
	v_permlane16_swap_b32_e32 v108, v98
	v_add_f32_e32 v98, v108, v98
	v_mov_b32_e32 v99, v98
	s_nop 1
	v_permlane32_swap_b32_e32 v98, v99
	v_add_f32_e32 v165, v98, v99
	ds_write_b128 v209, v[134:137]
	ds_write_b128 v209, v[138:141] offset:1152
	ds_read_b128 v[98:101], v210
	s_waitcnt lgkmcnt(0)
	v_lshlrev_b32_e32 v102, 16, v98
	v_and_b32_e32 v98, 0xffff0000, v98
	v_add_f32_e32 v95, v95, v98
	v_and_b32_e32 v98, 0xffff0000, v99
	v_add_f32_e32 v97, v97, v98
	v_lshlrev_b32_e32 v98, 16, v100
	v_add_f32_e32 v98, v90, v98
	v_and_b32_e32 v90, 0xffff0000, v100
	v_lshlrev_b32_e32 v103, 16, v99
	v_add_f32_e32 v99, v91, v90
	v_lshlrev_b32_e32 v90, 16, v101
	v_add_f32_e32 v100, v92, v90
	v_and_b32_e32 v90, 0xffff0000, v101
	v_add_f32_e32 v94, v94, v102
	v_add_f32_e32 v96, v96, v103
	v_add_f32_e32 v101, v93, v90
	v_cvt_pk_bf16_f32 v90, v94, v95
	v_cvt_pk_bf16_f32 v91, v96, v97
	v_cvt_pk_bf16_f32 v92, v98, v99
	v_cvt_pk_bf16_f32 v93, v100, v101
	ds_write_b128 v210, v[90:93]
	v_mul_f32_e32 v90, v95, v95
	v_mul_f32_e32 v91, v97, v97
	v_fmac_f32_e32 v90, v94, v94
	v_fmac_f32_e32 v91, v96, v96
	v_add_f32_e32 v94, v90, v91
	ds_read_b128 v[90:93], v210 offset:64
	v_mul_f32_e32 v95, v99, v99
	v_mul_f32_e32 v96, v101, v101
	v_fmac_f32_e32 v95, v98, v98
	v_fmac_f32_e32 v96, v100, v100
	v_add_f32_e32 v95, v95, v96
	v_add_f32_e32 v94, v94, v95
	s_waitcnt lgkmcnt(0)
	v_lshlrev_b32_e32 v95, 16, v90
	v_and_b32_e32 v90, 0xffff0000, v90
	v_add_f32_e32 v87, v87, v90
	v_lshlrev_b32_e32 v90, 16, v91
	v_add_f32_e32 v88, v88, v90
	v_and_b32_e32 v90, 0xffff0000, v91
	v_add_f32_e32 v89, v89, v90
	v_lshlrev_b32_e32 v90, 16, v92
	v_add_f32_e32 v90, v82, v90
	v_and_b32_e32 v82, 0xffff0000, v92
	v_add_f32_e32 v91, v83, v82
	v_lshlrev_b32_e32 v82, 16, v93
	v_add_f32_e32 v92, v84, v82
	v_and_b32_e32 v82, 0xffff0000, v93
	v_add_f32_e32 v86, v86, v95
	v_add_f32_e32 v93, v85, v82
	v_cvt_pk_bf16_f32 v82, v86, v87
	v_cvt_pk_bf16_f32 v83, v88, v89
	v_cvt_pk_bf16_f32 v84, v90, v91
	v_cvt_pk_bf16_f32 v85, v92, v93
	ds_write_b128 v210, v[82:85] offset:64
	v_mul_f32_e32 v82, v87, v87
	v_mul_f32_e32 v83, v89, v89
	v_fmac_f32_e32 v82, v86, v86
	v_fmac_f32_e32 v83, v88, v88
	v_add_f32_e32 v82, v82, v83
	v_mul_f32_e32 v83, v91, v91
	v_mul_f32_e32 v84, v93, v93
	v_fmac_f32_e32 v83, v90, v90
	v_fmac_f32_e32 v84, v92, v92
	v_add_f32_e32 v83, v83, v84
	v_add_f32_e32 v82, v82, v83
	v_add_f32_e32 v92, v94, v82
	ds_read_b128 v[82:85], v211
	v_lshl_add_u64 v[86:87], s[76:77], 0, v[188:189]
	v_lshl_add_u64 v[86:87], v[86:87], 0, s[48:49]
	v_lshl_add_u64 v[90:91], v[86:87], 0, v[0:1]
	ds_read_b128 v[86:89], v211 offset:1152
	s_waitcnt lgkmcnt(1)
	global_store_dwordx4 v[90:91], v[82:85], off nt
	s_nop 1
	v_lshl_add_u64 v[82:83], s[76:77], 0, v[186:187]
	v_lshl_add_u64 v[82:83], v[82:83], 0, s[48:49]
	v_lshl_add_u64 v[82:83], v[82:83], 0, v[0:1]
	s_waitcnt lgkmcnt(0)
; #define PG8_LAS __attribute__((address_space(3)))
; __device__ __forceinline__ unsigned cvt_pk_bf16(float lo, float hi) { unsigned r; asm volatile("v_cvt_pk_bf16_f32 %0, %1, %2" : "=v"(r) : "v"(lo), "v"(hi)); return r; }
; __device__ __forceinline__ float sum_x16(float s) { auto r = __builtin_amdgcn_permlane16_swap(__float_as_uint(s), __float_as_uint(s), false, false); return __uint_as_float(r[0]) + __uint_as_float(r[1]); }
; __device__ __forceinline__ float sum_x32(float s) { auto r = __builtin_amdgcn_permlane32_swap(__float_as_uint(s), __float_as_uint(s), false, false); return __uint_as_float(r[0]) + __uint_as_float(r[1]); }
;     __device__ __forceinline__ void operator()(const f32x4 (&acc)[2][2][4][2], const Unit& u, int wr, int wc, int fr, int fq, PG8_LAS unsigned char* stg) const {
;     ...
;         for (int m = 0; m < 4; ++m) {
;             const int row = rowb + ai * HALF + m * 16 + fr;
; #pragma unroll
;             for (int i = 0; i < 2; ++i) { const int c = lane + 64 * i; *(PG8_LAS u32x4*)(stg + (c >> 3) * 144 + (c & 7) * 16) = xin[m][i]; }
;             float ss = 0.f;
; #pragma unroll
;             for (int bj = 0; bj < 2; ++bj) {
;                 const u32x4 xo = *(const PG8_LAS u32x4*)(st + bj * 64);
;                 float v[8];
; #pragma unroll
;                 for (int i = 0; i < 4; ++i) { v[2 * i] = __uint_as_float(xo[i] << 16) + acc[ai][bj][m][i >> 1][(2 * i) & 3]; v[2 * i + 1] = __uint_as_float(xo[i] & 0xffff0000u) + acc[ai][bj][m][i >> 1][(2 * i + 1) & 3]; }
;                 u32x4 w; w.x = cvt_pk_bf16(v[0], v[1]); w.y = cvt_pk_bf16(v[2], v[3]); w.z = cvt_pk_bf16(v[4], v[5]); w.w = cvt_pk_bf16(v[6], v[7]);
;                 *(PG8_LAS u32x4*)(st + bj * 64) = w;
;                 ss += ((v[0] * v[0] + v[1] * v[1]) + (v[2] * v[2] + v[3] * v[3])) + ((v[4] * v[4] + v[5] * v[5]) + (v[6] * v[6] + v[7] * v[7]));
;             }
; #pragma unroll
;             for (int i = 0; i < 2; ++i) { const int c = lane + 64 * i; const u32x4 w = *(const PG8_LAS u32x4*)(stg + (c >> 3) * 144 + (c & 7) * 16);
;                 *(u32x4*)(xo_ + (size_t)(row - fr + (c >> 3)) * 1024 + colw + (c & 7) * 8) = w; }
;             ss = sum_x16(ss); ss = sum_x32(ss);
;             if (fq == 0) po_[(size_t)(u.pn * 4 + wc) * 65536 + row] = ss;
	global_store_dwordx4 v[82:83], v[86:89], off nt
	v_mov_b32_e32 v82, v92
	s_nop 1
	v_permlane16_swap_b32_e32 v92, v82
	v_add_f32_e32 v82, v92, v82
	v_mov_b32_e32 v83, v82
	s_nop 1
	v_permlane32_swap_b32_e32 v82, v83
	v_readlane_b32 s55, v254, 41
	v_add_f32_e32 v166, v82, v83
	ds_write_b128 v209, v[130:133]
	ds_write_b128 v209, v[142:145] offset:1152
	ds_read_b128 v[82:85], v210
	s_waitcnt lgkmcnt(0)
	v_lshlrev_b32_e32 v86, 16, v82
	v_and_b32_e32 v82, 0xffff0000, v82
	v_add_f32_e32 v79, v79, v82
	v_and_b32_e32 v82, 0xffff0000, v83
	v_add_f32_e32 v81, v81, v82
	v_lshlrev_b32_e32 v82, 16, v84
	v_add_f32_e32 v82, v74, v82
	v_and_b32_e32 v74, 0xffff0000, v84
	v_lshlrev_b32_e32 v87, 16, v83
	v_add_f32_e32 v83, v75, v74
	v_lshlrev_b32_e32 v74, 16, v85
	v_add_f32_e32 v84, v76, v74
	v_and_b32_e32 v74, 0xffff0000, v85
	v_add_f32_e32 v78, v78, v86
	v_add_f32_e32 v80, v80, v87
	v_add_f32_e32 v85, v77, v74
	v_cvt_pk_bf16_f32 v74, v78, v79
	v_cvt_pk_bf16_f32 v75, v80, v81
	v_cvt_pk_bf16_f32 v76, v82, v83
	v_cvt_pk_bf16_f32 v77, v84, v85
	ds_write_b128 v210, v[74:77]
	v_mul_f32_e32 v74, v79, v79
	v_mul_f32_e32 v75, v81, v81
	v_fmac_f32_e32 v74, v78, v78
	v_fmac_f32_e32 v75, v80, v80
	v_add_f32_e32 v78, v74, v75
	ds_read_b128 v[74:77], v210 offset:64
	v_mul_f32_e32 v79, v83, v83
	v_mul_f32_e32 v80, v85, v85
	v_fmac_f32_e32 v79, v82, v82
	v_fmac_f32_e32 v80, v84, v84
	v_add_f32_e32 v79, v79, v80
	v_add_f32_e32 v78, v78, v79
	s_waitcnt lgkmcnt(0)
	v_lshlrev_b32_e32 v79, 16, v74
	v_and_b32_e32 v74, 0xffff0000, v74
	v_add_f32_e32 v71, v71, v74
	v_lshlrev_b32_e32 v74, 16, v75
	v_add_f32_e32 v72, v72, v74
	v_and_b32_e32 v74, 0xffff0000, v75
	v_add_f32_e32 v73, v73, v74
	v_lshlrev_b32_e32 v74, 16, v76
	v_add_f32_e32 v74, v66, v74
	v_and_b32_e32 v66, 0xffff0000, v76
	v_add_f32_e32 v75, v67, v66
	v_lshlrev_b32_e32 v66, 16, v77
	v_add_f32_e32 v76, v68, v66
	v_and_b32_e32 v66, 0xffff0000, v77
	v_add_f32_e32 v70, v70, v79
	v_add_f32_e32 v77, v69, v66
	v_cvt_pk_bf16_f32 v66, v70, v71
	v_cvt_pk_bf16_f32 v67, v72, v73
	v_cvt_pk_bf16_f32 v68, v74, v75
	v_cvt_pk_bf16_f32 v69, v76, v77
	ds_write_b128 v210, v[66:69] offset:64
	v_mul_f32_e32 v66, v71, v71
	v_mul_f32_e32 v67, v73, v73
	v_fmac_f32_e32 v66, v70, v70
	v_fmac_f32_e32 v67, v72, v72
	v_add_f32_e32 v66, v66, v67
	v_mul_f32_e32 v67, v75, v75
	v_mul_f32_e32 v68, v77, v77
	v_fmac_f32_e32 v67, v74, v74
	v_fmac_f32_e32 v68, v76, v76
	v_add_f32_e32 v67, v67, v68
	v_add_f32_e32 v66, v66, v67
	v_add_f32_e32 v76, v78, v66
	ds_read_b128 v[66:69], v211
	v_lshl_add_u64 v[70:71], s[76:77], 0, v[184:185]
	v_lshl_add_u64 v[70:71], v[70:71], 0, s[48:49]
	v_lshl_add_u64 v[74:75], v[70:71], 0, v[0:1]
	ds_read_b128 v[70:73], v211 offset:1152
	s_waitcnt lgkmcnt(1)
	global_store_dwordx4 v[74:75], v[66:69], off nt
	s_nop 1
	v_lshl_add_u64 v[66:67], s[76:77], 0, v[190:191]
	v_lshl_add_u64 v[66:67], v[66:67], 0, s[48:49]
	v_lshl_add_u64 v[66:67], v[66:67], 0, v[0:1]
	s_waitcnt lgkmcnt(0)
	global_store_dwordx4 v[66:67], v[70:73], off nt
	v_mov_b32_e32 v66, v76
	s_nop 1
	v_permlane16_swap_b32_e32 v76, v66
	v_add_f32_e32 v66, v76, v66
	v_mov_b32_e32 v67, v66
	s_nop 1
	v_permlane32_swap_b32_e32 v66, v67
	v_add_f32_e32 v167, v66, v67
	v_mbcnt_lo_u32_b32 v200, -1, 0
	v_mbcnt_hi_u32_b32 v200, -1, v200
	v_lshrrev_b32_e32 v201, 4, v200
	v_cmp_eq_u32_e64 s[100:101], 1, v201
	s_nop 1
	v_cndmask_b32_e64 v212, v164, v165, s[100:101]
	v_cmp_eq_u32_e64 s[100:101], 2, v201
	s_nop 1
	v_cndmask_b32_e64 v212, v212, v166, s[100:101]
	v_cmp_eq_u32_e64 s[100:101], 3, v201
	s_nop 1
	v_cndmask_b32_e64 v212, v212, v167, s[100:101]
	s_nop 1
	s_add_u32 s100, s82, s46
	s_addc_u32 s101, s83, s47
	v_or_b32_e32 v201, s44, v174
	v_lshlrev_b32_e32 v201, 2, v201
	v_and_b32_e32 v200, 48, v200
	v_lshl_add_u32 v201, v200, 2, v201
	global_store_dword v201, v212, s[100:101] offset:0
	s_add_i32 s29, s44, 0x80
	v_or_b32_e32 v66, s29, v206
	v_ashrrev_i32_e32 v67, 31, v66
	v_lshlrev_b64 v[104:105], 11, v[66:67]
	v_lshl_add_u64 v[66:67], v[182:183], 0, v[104:105]
	global_load_dwordx4 v[106:109], v[66:67], off
	v_or_b32_e32 v66, s29, v207
	v_ashrrev_i32_e32 v67, 31, v66
	v_lshlrev_b64 v[102:103], 11, v[66:67]
	v_lshl_add_u64 v[66:67], v[182:183], 0, v[102:103]
	global_load_dwordx4 v[110:113], v[66:67], off
	s_add_i32 s29, s44, 0x90
	v_or_b32_e32 v66, s29, v206
	v_ashrrev_i32_e32 v67, 31, v66
	v_lshlrev_b64 v[100:101], 11, v[66:67]
	v_lshl_add_u64 v[66:67], v[182:183], 0, v[100:101]
	global_load_dwordx4 v[82:85], v[66:67], off
	v_or_b32_e32 v66, s29, v207
	v_ashrrev_i32_e32 v67, 31, v66
	v_lshlrev_b64 v[98:99], 11, v[66:67]
	v_lshl_add_u64 v[66:67], v[182:183], 0, v[98:99]
	s_add_i32 s29, s44, 0xa0
	global_load_dwordx4 v[86:89], v[66:67], off
	v_or_b32_e32 v66, s29, v206
	v_ashrrev_i32_e32 v67, 31, v66
	v_lshlrev_b64 v[94:95], 11, v[66:67]
	v_lshl_add_u64 v[66:67], v[182:183], 0, v[94:95]
	global_load_dwordx4 v[70:73], v[66:67], off
	v_or_b32_e32 v66, s29, v207
	v_ashrrev_i32_e32 v67, 31, v66
	v_lshlrev_b64 v[92:93], 11, v[66:67]
	v_lshl_add_u64 v[66:67], v[182:183], 0, v[92:93]
	s_add_i32 s29, s44, 0xb0
	global_load_dwordx4 v[74:77], v[66:67], off
	v_or_b32_e32 v66, s29, v206
	v_or_b32_e32 v78, s29, v207
	v_ashrrev_i32_e32 v67, 31, v66
	v_ashrrev_i32_e32 v79, 31, v78
	v_lshlrev_b64 v[90:91], 11, v[66:67]
	v_lshlrev_b64 v[96:97], 11, v[78:79]
	v_lshl_add_u64 v[66:67], v[182:183], 0, v[90:91]
	v_lshl_add_u64 v[78:79], v[182:183], 0, v[96:97]
	global_load_dwordx4 v[66:69], v[66:67], off
	s_nop 0
	global_load_dwordx4 v[78:81], v[78:79], off
	s_waitcnt vmcnt(7)
	ds_write_b128 v209, v[106:109]
	s_waitcnt vmcnt(6)
	ds_write_b128 v209, v[110:113] offset:1152
	ds_read_b128 v[106:109], v210
	s_waitcnt lgkmcnt(0)
; #define PG8_LAS __attribute__((address_space(3)))
; __device__ __forceinline__ unsigned cvt_pk_bf16(float lo, float hi) { unsigned r; asm volatile("v_cvt_pk_bf16_f32 %0, %1, %2" : "=v"(r) : "v"(lo), "v"(hi)); return r; }
; __device__ __forceinline__ float sum_x16(float s) { auto r = __builtin_amdgcn_permlane16_swap(__float_as_uint(s), __float_as_uint(s), false, false); return __uint_as_float(r[0]) + __uint_as_float(r[1]); }
; __device__ __forceinline__ float sum_x32(float s) { auto r = __builtin_amdgcn_permlane32_swap(__float_as_uint(s), __float_as_uint(s), false, false); return __uint_as_float(r[0]) + __uint_as_float(r[1]); }
;     __device__ __forceinline__ void operator()(const f32x4 (&acc)[2][2][4][2], const Unit& u, int wr, int wc, int fr, int fq, PG8_LAS unsigned char* stg) const {
;     ...
;         for (int m = 0; m < 4; ++m) {
;             const int row = rowb + ai * HALF + m * 16 + fr;
; #pragma unroll
;             for (int i = 0; i < 2; ++i) { const int c = lane + 64 * i; *(PG8_LAS u32x4*)(stg + (c >> 3) * 144 + (c & 7) * 16) = xin[m][i]; }
;             float ss = 0.f;
; #pragma unroll
;             for (int bj = 0; bj < 2; ++bj) {
;                 const u32x4 xo = *(const PG8_LAS u32x4*)(st + bj * 64);
;                 float v[8];
; #pragma unroll
;                 for (int i = 0; i < 4; ++i) { v[2 * i] = __uint_as_float(xo[i] << 16) + acc[ai][bj][m][i >> 1][(2 * i) & 3]; v[2 * i + 1] = __uint_as_float(xo[i] & 0xffff0000u) + acc[ai][bj][m][i >> 1][(2 * i + 1) & 3]; }
;                 u32x4 w; w.x = cvt_pk_bf16(v[0], v[1]); w.y = cvt_pk_bf16(v[2], v[3]); w.z = cvt_pk_bf16(v[4], v[5]); w.w = cvt_pk_bf16(v[6], v[7]);
;                 *(PG8_LAS u32x4*)(st + bj * 64) = w;
;                 ss += ((v[0] * v[0] + v[1] * v[1]) + (v[2] * v[2] + v[3] * v[3])) + ((v[4] * v[4] + v[5] * v[5]) + (v[6] * v[6] + v[7] * v[7]));
;             }
; #pragma unroll
;             for (int i = 0; i < 2; ++i) { const int c = lane + 64 * i; const u32x4 w = *(const PG8_LAS u32x4*)(stg + (c >> 3) * 144 + (c & 7) * 16);
;                 *(u32x4*)(xo_ + (size_t)(row - fr + (c >> 3)) * 1024 + colw + (c & 7) * 8) = w; }
;             ss = sum_x16(ss); ss = sum_x32(ss);
;             if (fq == 0) po_[(size_t)(u.pn * 4 + wc) * 65536 + row] = ss;
	v_lshlrev_b32_e32 v110, 16, v106
	v_and_b32_e32 v106, 0xffff0000, v106
	v_add_f32_e32 v63, v63, v106
	v_lshlrev_b32_e32 v106, 16, v107
	v_add_f32_e32 v64, v64, v106
	v_and_b32_e32 v106, 0xffff0000, v107
	v_add_f32_e32 v65, v65, v106
	v_lshlrev_b32_e32 v106, 16, v108
	v_add_f32_e32 v106, v58, v106
	v_and_b32_e32 v58, 0xffff0000, v108
	v_add_f32_e32 v107, v59, v58
	v_lshlrev_b32_e32 v58, 16, v109
	v_add_f32_e32 v108, v60, v58
	v_and_b32_e32 v58, 0xffff0000, v109
	v_add_f32_e32 v62, v62, v110
	v_add_f32_e32 v109, v61, v58
	v_cvt_pk_bf16_f32 v58, v62, v63
	v_cvt_pk_bf16_f32 v59, v64, v65
	v_cvt_pk_bf16_f32 v60, v106, v107
	v_cvt_pk_bf16_f32 v61, v108, v109
	ds_write_b128 v210, v[58:61]
	v_mul_f32_e32 v58, v63, v63
	v_mul_f32_e32 v59, v65, v65
	v_fmac_f32_e32 v58, v62, v62
	v_fmac_f32_e32 v59, v64, v64
	v_add_f32_e32 v58, v58, v59
	v_mul_f32_e32 v59, v107, v107
	v_mul_f32_e32 v60, v109, v109
	v_fmac_f32_e32 v59, v106, v106
	v_fmac_f32_e32 v60, v108, v108
	v_add_f32_e32 v59, v59, v60
	v_add_f32_e32 v62, v58, v59
	ds_read_b128 v[58:61], v210 offset:64
	s_waitcnt lgkmcnt(0)
	v_lshlrev_b32_e32 v63, 16, v58
	v_and_b32_e32 v58, 0xffff0000, v58
	v_add_f32_e32 v55, v55, v58
	v_lshlrev_b32_e32 v58, 16, v59
	v_add_f32_e32 v56, v56, v58
	v_and_b32_e32 v58, 0xffff0000, v59
	v_add_f32_e32 v57, v57, v58
	v_lshlrev_b32_e32 v58, 16, v60
	v_add_f32_e32 v58, v50, v58
	v_and_b32_e32 v50, 0xffff0000, v60
	v_add_f32_e32 v59, v51, v50
	v_lshlrev_b32_e32 v50, 16, v61
	v_add_f32_e32 v60, v52, v50
	v_and_b32_e32 v50, 0xffff0000, v61
	v_add_f32_e32 v54, v54, v63
	v_add_f32_e32 v61, v53, v50
	v_cvt_pk_bf16_f32 v50, v54, v55
	v_cvt_pk_bf16_f32 v51, v56, v57
	v_cvt_pk_bf16_f32 v52, v58, v59
	v_cvt_pk_bf16_f32 v53, v60, v61
	ds_write_b128 v210, v[50:53] offset:64
	v_mul_f32_e32 v50, v55, v55
	v_mul_f32_e32 v51, v57, v57
	v_fmac_f32_e32 v50, v54, v54
	v_fmac_f32_e32 v51, v56, v56
	v_add_f32_e32 v50, v50, v51
	v_mul_f32_e32 v51, v59, v59
	v_mul_f32_e32 v52, v61, v61
	v_fmac_f32_e32 v51, v58, v58
	v_fmac_f32_e32 v52, v60, v60
	v_add_f32_e32 v51, v51, v52
	v_add_f32_e32 v50, v50, v51
	v_add_f32_e32 v56, v62, v50
	ds_read_b128 v[50:53], v211
	v_lshl_add_u64 v[54:55], s[76:77], 0, v[104:105]
	v_lshl_add_u64 v[54:55], v[54:55], 0, s[48:49]
	v_lshl_add_u64 v[54:55], v[54:55], 0, v[0:1]
	s_waitcnt lgkmcnt(0)
	global_store_dwordx4 v[54:55], v[50:53], off nt
	ds_read_b128 v[50:53], v211 offset:1152
	v_lshl_add_u64 v[54:55], s[76:77], 0, v[102:103]
	v_lshl_add_u64 v[54:55], v[54:55], 0, s[48:49]
	v_lshl_add_u64 v[54:55], v[54:55], 0, v[0:1]
	s_waitcnt lgkmcnt(0)
	global_store_dwordx4 v[54:55], v[50:53], off nt
	s_nop 1
	v_mov_b32_e32 v50, v56
	s_nop 1
	v_permlane16_swap_b32_e32 v56, v50
	v_add_f32_e32 v50, v56, v50
	v_mov_b32_e32 v51, v50
	s_nop 1
	v_permlane32_swap_b32_e32 v50, v51
	v_add_f32_e32 v164, v50, v51
	s_waitcnt vmcnt(7)
	ds_write_b128 v209, v[82:85]
	s_waitcnt vmcnt(6)
	ds_write_b128 v209, v[86:89] offset:1152
	ds_read_b128 v[50:53], v210
	s_waitcnt lgkmcnt(0)
	v_lshlrev_b32_e32 v54, 16, v50
	v_and_b32_e32 v50, 0xffff0000, v50
	v_add_f32_e32 v47, v47, v50
	v_and_b32_e32 v50, 0xffff0000, v51
	v_add_f32_e32 v49, v49, v50
	v_lshlrev_b32_e32 v50, 16, v52
	v_add_f32_e32 v50, v42, v50
	v_and_b32_e32 v42, 0xffff0000, v52
	v_lshlrev_b32_e32 v55, 16, v51
	v_add_f32_e32 v51, v43, v42
	v_lshlrev_b32_e32 v42, 16, v53
	v_add_f32_e32 v52, v44, v42
	v_and_b32_e32 v42, 0xffff0000, v53
	v_add_f32_e32 v46, v46, v54
	v_add_f32_e32 v48, v48, v55
	v_add_f32_e32 v53, v45, v42
	v_cvt_pk_bf16_f32 v42, v46, v47
	v_cvt_pk_bf16_f32 v43, v48, v49
	v_cvt_pk_bf16_f32 v44, v50, v51
	v_cvt_pk_bf16_f32 v45, v52, v53
	ds_write_b128 v210, v[42:45]
	v_mul_f32_e32 v42, v47, v47
	v_mul_f32_e32 v43, v49, v49
	v_fmac_f32_e32 v42, v46, v46
	v_fmac_f32_e32 v43, v48, v48
	v_add_f32_e32 v46, v42, v43
	ds_read_b128 v[42:45], v210 offset:64
	v_mul_f32_e32 v47, v51, v51
	v_mul_f32_e32 v48, v53, v53
	v_fmac_f32_e32 v47, v50, v50
	v_fmac_f32_e32 v48, v52, v52
	v_add_f32_e32 v47, v47, v48
	v_add_f32_e32 v46, v46, v47
	s_waitcnt lgkmcnt(0)
	v_lshlrev_b32_e32 v47, 16, v42
	v_and_b32_e32 v42, 0xffff0000, v42
	v_add_f32_e32 v39, v39, v42
	v_lshlrev_b32_e32 v42, 16, v43
	v_add_f32_e32 v40, v40, v42
	v_and_b32_e32 v42, 0xffff0000, v43
	v_add_f32_e32 v41, v41, v42
	v_lshlrev_b32_e32 v42, 16, v44
	v_add_f32_e32 v42, v34, v42
	v_and_b32_e32 v34, 0xffff0000, v44
	v_add_f32_e32 v43, v35, v34
	v_lshlrev_b32_e32 v34, 16, v45
	v_add_f32_e32 v44, v36, v34
	v_and_b32_e32 v34, 0xffff0000, v45
	v_add_f32_e32 v38, v38, v47
	v_add_f32_e32 v45, v37, v34
	v_cvt_pk_bf16_f32 v34, v38, v39
	v_cvt_pk_bf16_f32 v35, v40, v41
	v_cvt_pk_bf16_f32 v36, v42, v43
	v_cvt_pk_bf16_f32 v37, v44, v45
	ds_write_b128 v210, v[34:37] offset:64
	v_mul_f32_e32 v34, v39, v39
	v_mul_f32_e32 v35, v41, v41
	v_fmac_f32_e32 v34, v38, v38
	v_fmac_f32_e32 v35, v40, v40
	v_add_f32_e32 v34, v34, v35
	v_mul_f32_e32 v35, v43, v43
	v_mul_f32_e32 v36, v45, v45
	v_fmac_f32_e32 v35, v42, v42
	v_fmac_f32_e32 v36, v44, v44
	v_add_f32_e32 v35, v35, v36
	v_add_f32_e32 v34, v34, v35
	v_add_f32_e32 v44, v46, v34
	ds_read_b128 v[34:37], v211
	v_lshl_add_u64 v[38:39], s[76:77], 0, v[100:101]
	v_lshl_add_u64 v[38:39], v[38:39], 0, s[48:49]
	v_lshl_add_u64 v[42:43], v[38:39], 0, v[0:1]
	ds_read_b128 v[38:41], v211 offset:1152
	s_waitcnt lgkmcnt(1)
	global_store_dwordx4 v[42:43], v[34:37], off nt
	s_nop 1
	v_lshl_add_u64 v[34:35], s[76:77], 0, v[98:99]
	v_lshl_add_u64 v[34:35], v[34:35], 0, s[48:49]
	v_lshl_add_u64 v[34:35], v[34:35], 0, v[0:1]
	s_waitcnt lgkmcnt(0)
; #define PG8_LAS __attribute__((address_space(3)))
;     __device__ __forceinline__ void operator()(const f32x4 (&acc)[2][2][4][2], const Unit& u, int wr, int wc, int fr, int fq, PG8_LAS unsigned char* stg) const {
;     ...
;         for (int m = 0; m < 4; ++m) {
;             const int row = rowb + ai * HALF + m * 16 + fr;
; #pragma unroll
;             for (int i = 0; i < 2; ++i) { const int c = lane + 64 * i; *(PG8_LAS u32x4*)(stg + (c >> 3) * 144 + (c & 7) * 16) = xin[m][i]; }
;             float ss = 0.f;
; #pragma unroll
;             for (int bj = 0; bj < 2; ++bj) {
;                 const u32x4 xo = *(const PG8_LAS u32x4*)(st + bj * 64);
;                 float v[8];
; #pragma unroll
;                 for (int i = 0; i < 4; ++i) { v[2 * i] = __uint_as_float(xo[i] << 16) + acc[ai][bj][m][i >> 1][(2 * i) & 3]; v[2 * i + 1] = __uint_as_float(xo[i] & 0xffff0000u) + acc[ai][bj][m][i >> 1][(2 * i + 1) & 3]; }
;                 u32x4 w; w.x = cvt_pk_bf16(v[0], v[1]); w.y = cvt_pk_bf16(v[2], v[3]); w.z = cvt_pk_bf16(v[4], v[5]); w.w = cvt_pk_bf16(v[6], v[7]);
;                 *(PG8_LAS u32x4*)(st + bj * 64) = w;
;                 ss += ((v[0] * v[0] + v[1] * v[1]) + (v[2] * v[2] + v[3] * v[3])) + ((v[4] * v[4] + v[5] * v[5]) + (v[6] * v[6] + v[7] * v[7]));
;             }
; #pragma unroll
;             for (int i = 0; i < 2; ++i) { const int c = lane + 64 * i; const u32x4 w = *(const PG8_LAS u32x4*)(stg + (c >> 3) * 144 + (c & 7) * 16);
;                 *(u32x4*)(xo_ + (size_t)(row - fr + (c >> 3)) * 1024 + colw + (c & 7) * 8) = w; }
;             ss = sum_x16(ss); ss = sum_x32(ss);
;             if (fq == 0) po_[(size_t)(u.pn * 4 + wc) * 65536 + row] = ss;
; template <class Epi, class Sched, bool ALIGN_EPI = false, bool SP2 = false>
; __device__ __forceinline__ void gemm_phase(PG8_LAS unsigned char* lds, const Gemm g, const Sched& S, const Epi& E, const int wave_s) {
;     ...
;         if (!has_next) break;
; #pragma unroll
;         for (int a = 0; a < 2; ++a)
; #pragma unroll
;             for (int b = 0; b < 2; ++b)
; #pragma unroll
;                 for (int m = 0; m < 4; ++m)
; #pragma unroll
;                     for (int n = 0; n < 2; ++n) acc[a][b][m][n] = (f32x4){0.f, 0.f, 0.f, 0.f};
;         if (nxt.pm != cur.pm) rs_par ^= 1;
;         cur = nxt; cA = nA; cB = nB; ++ui;
;         if constexpr (ALIGN_EPI) { if (wr == 1) PG8_BAR; }
	global_store_dwordx4 v[34:35], v[38:41], off nt
	v_mov_b32_e32 v34, v44
	s_nop 1
	v_permlane16_swap_b32_e32 v44, v34
	v_add_f32_e32 v34, v44, v34
	v_mov_b32_e32 v35, v34
	s_nop 1
	v_permlane32_swap_b32_e32 v34, v35
	v_add_f32_e32 v165, v34, v35
	s_waitcnt vmcnt(7)
	ds_write_b128 v209, v[70:73]
	s_waitcnt vmcnt(6)
	ds_write_b128 v209, v[74:77] offset:1152
	ds_read_b128 v[34:37], v210
	s_waitcnt lgkmcnt(0)
	v_lshlrev_b32_e32 v38, 16, v34
	v_and_b32_e32 v34, 0xffff0000, v34
	v_add_f32_e32 v31, v31, v34
	v_and_b32_e32 v34, 0xffff0000, v35
	v_add_f32_e32 v33, v33, v34
	v_lshlrev_b32_e32 v34, 16, v36
	v_add_f32_e32 v34, v26, v34
	v_and_b32_e32 v26, 0xffff0000, v36
	v_lshlrev_b32_e32 v39, 16, v35
	v_add_f32_e32 v35, v27, v26
	v_lshlrev_b32_e32 v26, 16, v37
	v_add_f32_e32 v36, v28, v26
	v_and_b32_e32 v26, 0xffff0000, v37
	v_add_f32_e32 v30, v30, v38
	v_add_f32_e32 v32, v32, v39
	v_add_f32_e32 v37, v29, v26
	v_cvt_pk_bf16_f32 v26, v30, v31
	v_cvt_pk_bf16_f32 v27, v32, v33
	v_cvt_pk_bf16_f32 v28, v34, v35
	v_cvt_pk_bf16_f32 v29, v36, v37
	ds_write_b128 v210, v[26:29]
	v_mul_f32_e32 v26, v31, v31
	v_mul_f32_e32 v27, v33, v33
	v_fmac_f32_e32 v26, v30, v30
	v_fmac_f32_e32 v27, v32, v32
	v_add_f32_e32 v30, v26, v27
	ds_read_b128 v[26:29], v210 offset:64
	v_mul_f32_e32 v31, v35, v35
	v_mul_f32_e32 v32, v37, v37
	v_fmac_f32_e32 v31, v34, v34
	v_fmac_f32_e32 v32, v36, v36
	v_add_f32_e32 v31, v31, v32
	v_add_f32_e32 v30, v30, v31
	s_waitcnt lgkmcnt(0)
	v_lshlrev_b32_e32 v31, 16, v26
	v_and_b32_e32 v26, 0xffff0000, v26
	v_add_f32_e32 v23, v23, v26
	v_lshlrev_b32_e32 v26, 16, v27
	v_add_f32_e32 v24, v24, v26
	v_and_b32_e32 v26, 0xffff0000, v27
	v_add_f32_e32 v25, v25, v26
	v_lshlrev_b32_e32 v26, 16, v28
	v_add_f32_e32 v26, v18, v26
	v_and_b32_e32 v18, 0xffff0000, v28
	v_add_f32_e32 v27, v19, v18
	v_lshlrev_b32_e32 v18, 16, v29
	v_add_f32_e32 v28, v20, v18
	v_and_b32_e32 v18, 0xffff0000, v29
	v_add_f32_e32 v22, v22, v31
	v_add_f32_e32 v29, v21, v18
	v_cvt_pk_bf16_f32 v18, v22, v23
	v_cvt_pk_bf16_f32 v19, v24, v25
	v_cvt_pk_bf16_f32 v20, v26, v27
	v_cvt_pk_bf16_f32 v21, v28, v29
	ds_write_b128 v210, v[18:21] offset:64
	v_mul_f32_e32 v18, v23, v23
	v_mul_f32_e32 v19, v25, v25
	v_fmac_f32_e32 v18, v22, v22
	v_fmac_f32_e32 v19, v24, v24
	v_add_f32_e32 v18, v18, v19
	v_mul_f32_e32 v19, v27, v27
	v_mul_f32_e32 v20, v29, v29
	v_fmac_f32_e32 v19, v26, v26
	v_fmac_f32_e32 v20, v28, v28
	v_add_f32_e32 v19, v19, v20
	v_add_f32_e32 v18, v18, v19
	v_add_f32_e32 v28, v30, v18
	ds_read_b128 v[18:21], v211
	v_lshl_add_u64 v[22:23], s[76:77], 0, v[94:95]
	v_lshl_add_u64 v[22:23], v[22:23], 0, s[48:49]
	v_lshl_add_u64 v[26:27], v[22:23], 0, v[0:1]
	ds_read_b128 v[22:25], v211 offset:1152
	s_waitcnt lgkmcnt(1)
	global_store_dwordx4 v[26:27], v[18:21], off nt
	s_nop 1
	v_lshl_add_u64 v[18:19], s[76:77], 0, v[92:93]
	v_lshl_add_u64 v[18:19], v[18:19], 0, s[48:49]
	v_lshl_add_u64 v[18:19], v[18:19], 0, v[0:1]
	s_waitcnt lgkmcnt(0)
	global_store_dwordx4 v[18:19], v[22:25], off nt
	v_mov_b32_e32 v18, v28
	s_nop 1
	v_permlane16_swap_b32_e32 v28, v18
	v_add_f32_e32 v18, v28, v18
	v_mov_b32_e32 v19, v18
	s_nop 1
	v_permlane32_swap_b32_e32 v18, v19
	v_add_f32_e32 v166, v18, v19
	s_waitcnt vmcnt(7)
	ds_write_b128 v209, v[66:69]
	s_waitcnt vmcnt(6)
	ds_write_b128 v209, v[78:81] offset:1152
	ds_read_b128 v[18:21], v210
	s_waitcnt lgkmcnt(0)
	v_lshlrev_b32_e32 v22, 16, v18
	v_and_b32_e32 v18, 0xffff0000, v18
	v_add_f32_e32 v15, v15, v18
	v_and_b32_e32 v18, 0xffff0000, v19
	v_add_f32_e32 v17, v17, v18
	v_lshlrev_b32_e32 v18, 16, v20
	v_add_f32_e32 v18, v10, v18
	v_and_b32_e32 v10, 0xffff0000, v20
	v_lshlrev_b32_e32 v23, 16, v19
	v_add_f32_e32 v19, v11, v10
	v_lshlrev_b32_e32 v10, 16, v21
	v_add_f32_e32 v20, v12, v10
	v_and_b32_e32 v10, 0xffff0000, v21
	v_add_f32_e32 v14, v14, v22
	v_add_f32_e32 v16, v16, v23
	v_add_f32_e32 v21, v13, v10
	v_cvt_pk_bf16_f32 v10, v14, v15
	v_cvt_pk_bf16_f32 v11, v16, v17
	v_cvt_pk_bf16_f32 v12, v18, v19
	v_cvt_pk_bf16_f32 v13, v20, v21
	ds_write_b128 v210, v[10:13]
	v_mul_f32_e32 v10, v15, v15
	v_mul_f32_e32 v11, v17, v17
	v_fmac_f32_e32 v10, v14, v14
	v_fmac_f32_e32 v11, v16, v16
	v_add_f32_e32 v14, v10, v11
	ds_read_b128 v[10:13], v210 offset:64
	v_mul_f32_e32 v15, v19, v19
	v_mul_f32_e32 v16, v21, v21
	v_fmac_f32_e32 v15, v18, v18
	v_fmac_f32_e32 v16, v20, v20
	v_add_f32_e32 v15, v15, v16
	v_add_f32_e32 v14, v14, v15
	s_waitcnt lgkmcnt(0)
	v_lshlrev_b32_e32 v15, 16, v10
	v_and_b32_e32 v10, 0xffff0000, v10
	v_add_f32_e32 v7, v7, v10
	v_lshlrev_b32_e32 v10, 16, v11
	v_add_f32_e32 v8, v8, v10
	v_and_b32_e32 v10, 0xffff0000, v11
	v_add_f32_e32 v9, v9, v10
	v_lshlrev_b32_e32 v10, 16, v12
	v_add_f32_e32 v10, v2, v10
	v_and_b32_e32 v2, 0xffff0000, v12
	v_add_f32_e32 v11, v3, v2
	v_lshlrev_b32_e32 v2, 16, v13
	v_add_f32_e32 v12, v4, v2
	v_and_b32_e32 v2, 0xffff0000, v13
	v_add_f32_e32 v6, v6, v15
	v_add_f32_e32 v13, v5, v2
	v_cvt_pk_bf16_f32 v2, v6, v7
	v_cvt_pk_bf16_f32 v3, v8, v9
	v_cvt_pk_bf16_f32 v4, v10, v11
	v_cvt_pk_bf16_f32 v5, v12, v13
	ds_write_b128 v210, v[2:5] offset:64
	v_mul_f32_e32 v2, v7, v7
	v_mul_f32_e32 v3, v9, v9
	v_fmac_f32_e32 v2, v6, v6
	v_fmac_f32_e32 v3, v8, v8
	v_add_f32_e32 v2, v2, v3
	v_mul_f32_e32 v3, v11, v11
	v_mul_f32_e32 v4, v13, v13
	v_fmac_f32_e32 v3, v10, v10
	v_fmac_f32_e32 v4, v12, v12
	v_add_f32_e32 v3, v3, v4
	v_add_f32_e32 v2, v2, v3
	v_add_f32_e32 v12, v14, v2
	ds_read_b128 v[2:5], v211
	v_lshl_add_u64 v[6:7], s[76:77], 0, v[90:91]
	v_lshl_add_u64 v[6:7], v[6:7], 0, s[48:49]
	v_lshl_add_u64 v[10:11], v[6:7], 0, v[0:1]
	ds_read_b128 v[6:9], v211 offset:1152
	s_waitcnt lgkmcnt(1)
	global_store_dwordx4 v[10:11], v[2:5], off nt
	s_nop 1
	v_lshl_add_u64 v[2:3], s[76:77], 0, v[96:97]
	v_lshl_add_u64 v[2:3], v[2:3], 0, s[48:49]
	v_lshl_add_u64 v[2:3], v[2:3], 0, v[0:1]
	s_waitcnt lgkmcnt(0)
	global_store_dwordx4 v[2:3], v[6:9], off nt
	v_mov_b32_e32 v2, v12
	s_nop 1
	v_permlane16_swap_b32_e32 v12, v2
	v_add_f32_e32 v2, v12, v2
	v_mov_b32_e32 v3, v2
	s_nop 1
	v_permlane32_swap_b32_e32 v2, v3
	v_add_f32_e32 v167, v2, v3
	v_mbcnt_lo_u32_b32 v200, -1, 0
	v_mbcnt_hi_u32_b32 v200, -1, v200
	v_lshrrev_b32_e32 v201, 4, v200
	v_cmp_eq_u32_e64 s[100:101], 1, v201
	s_nop 1
	v_cndmask_b32_e64 v212, v164, v165, s[100:101]
	v_cmp_eq_u32_e64 s[100:101], 2, v201
	s_nop 1
	v_cndmask_b32_e64 v212, v212, v166, s[100:101]
	v_cmp_eq_u32_e64 s[100:101], 3, v201
	s_nop 1
	v_cndmask_b32_e64 v212, v212, v167, s[100:101]
	s_nop 1
	s_add_u32 s100, s82, s46
	s_addc_u32 s101, s83, s47
	v_or_b32_e32 v201, s44, v174
	v_lshlrev_b32_e32 v201, 2, v201
	v_and_b32_e32 v200, 48, v200
	v_lshl_add_u32 v201, v200, 2, v201
	global_store_dword v201, v212, s[100:101] offset:512
	s_andn2_b64 vcc, exec, s[36:37]
	s_mov_b64 s[36:37], -1
	s_cbranch_vccnz .LBB0_745
	s_andn2_b64 vcc, exec, s[18:19]
	s_cbranch_vccnz .LBB0_744
	s_barrier
	s_branch .LBB0_744

; #define PG8_LAS __attribute__((address_space(3)))
;     __device__ __forceinline__ void operator()(const f32x4 (&acc)[2][2][4][2], const Unit& u, int wr, int wc, int fr, int fq, PG8_LAS unsigned char* stg) const {
;         const int lane = fq * 16 + fr;
;         const size_t colw = (size_t)u.pn * BM + wc * 64;
;         const int rowb = u.pm * BM + wr * 64;
;         PG8_LAS unsigned char* st = stg + fr * 144 + fq * 16;
; #pragma unroll
;         for (int ai = 0; ai < 2; ++ai) {
;         asm volatile("" ::: "memory");
;         u32x4 xin[4][2];
; #pragma unroll
;         for (int m = 0; m < 4; ++m)
; #pragma unroll
;             for (int i = 0; i < 2; ++i) { const int c = lane + 64 * i; xin[m][i] = *(const u32x4*)(xb + (size_t)(rowb + ai * HALF + m * 16 + (c >> 3)) * 1024 + colw + (c & 7) * 8); }
; #pragma unroll
;         for (int m = 0; m < 4; ++m) {
;             const int row = rowb + ai * HALF + m * 16 + fr;
; #pragma unroll
;             for (int i = 0; i < 2; ++i) { const int c = lane + 64 * i; *(PG8_LAS u32x4*)(stg + (c >> 3) * 144 + (c & 7) * 16) = xin[m][i]; }
;             float ss = 0.f;
; #pragma unroll
;             for (int bj = 0; bj < 2; ++bj) {
;                 const u32x4 xo = *(const PG8_LAS u32x4*)(st + bj * 64);
;                 float v[8];
; #pragma unroll
;                 for (int i = 0; i < 4; ++i) { v[2 * i] = __uint_as_float(xo[i] << 16) + acc[ai][bj][m][i >> 1][(2 * i) & 3]; v[2 * i + 1] = __uint_as_float(xo[i] & 0xffff0000u) + acc[ai][bj][m][i >> 1][(2 * i + 1) & 3]; }
;                 u32x4 w; w.x = cvt_pk_bf16(v[0], v[1]); w.y = cvt_pk_bf16(v[2], v[3]); w.z = cvt_pk_bf16(v[4], v[5]); w.w = cvt_pk_bf16(v[6], v[7]);
;                 *(PG8_LAS u32x4*)(st + bj * 64) = w;
;                 ss += ((v[0] * v[0] + v[1] * v[1]) + (v[2] * v[2] + v[3] * v[3])) + ((v[4] * v[4] + v[5] * v[5]) + (v[6] * v[6] + v[7] * v[7]));
;             }
; #pragma unroll
;             for (int i = 0; i < 2; ++i) { const int c = lane + 64 * i; const u32x4 w = *(const PG8_LAS u32x4*)(stg + (c >> 3) * 144 + (c & 7) * 16);
;                 *(u32x4*)(xo_ + (size_t)(row - fr + (c >> 3)) * 1024 + colw + (c & 7) * 8) = w; }
;             ss = sum_x16(ss); ss = sum_x32(ss);
;             if (fq == 0) po_[(size_t)(u.pn * 4 + wc) * 65536 + row] = ss;
.LBB0_926:
	s_ashr_i32 s45, s44, 31
	s_lshl_b32 s14, s14, 8
	s_lshl_b64 s[16:17], s[44:45], 8
	s_add_i32 s42, s14, s10
	s_or_b64 s[16:17], s[16:17], s[74:75]
	v_or_b32_e32 v130, s42, v206
	s_lshl_b64 s[46:47], s[16:17], 1
	v_ashrrev_i32_e32 v131, 31, v130
	v_lshl_add_u64 v[182:183], v[176:177], 0, s[46:47]
	v_lshlrev_b64 v[198:199], 11, v[130:131]
	v_lshl_add_u64 v[130:131], v[182:183], 0, v[198:199]
	global_load_dwordx4 v[154:157], v[130:131], off
	v_or_b32_e32 v130, s42, v207
	v_ashrrev_i32_e32 v131, 31, v130
	v_lshlrev_b64 v[196:197], 11, v[130:131]
	v_lshl_add_u64 v[130:131], v[182:183], 0, v[196:197]
	global_load_dwordx4 v[160:163], v[130:131], off
	s_lshl_b32 s14, s44, 2
	s_or_b32 s14, s14, s9
	s_ashr_i32 s15, s14, 31
	s_lshl_b64 s[44:45], s[14:15], 18
	s_or_b32 s14, s42, 16
	v_or_b32_e32 v130, s14, v206
	v_ashrrev_i32_e32 v131, 31, v130
	v_lshlrev_b64 v[194:195], 11, v[130:131]
	v_lshl_add_u64 v[130:131], v[182:183], 0, v[194:195]
	global_load_dwordx4 v[146:149], v[130:131], off
	v_or_b32_e32 v130, s14, v207
	v_ashrrev_i32_e32 v131, 31, v130
	v_lshlrev_b64 v[192:193], 11, v[130:131]
	v_lshl_add_u64 v[130:131], v[182:183], 0, v[192:193]
	s_or_b32 s14, s42, 32
	global_load_dwordx4 v[150:153], v[130:131], off
	v_or_b32_e32 v130, s14, v206
	v_ashrrev_i32_e32 v131, 31, v130
	v_lshlrev_b64 v[188:189], 11, v[130:131]
	v_lshl_add_u64 v[130:131], v[182:183], 0, v[188:189]
	global_load_dwordx4 v[134:137], v[130:131], off
	v_or_b32_e32 v130, s14, v207
	v_ashrrev_i32_e32 v131, 31, v130
	v_lshlrev_b64 v[186:187], 11, v[130:131]
	v_lshl_add_u64 v[130:131], v[182:183], 0, v[186:187]
	s_or_b32 s14, s42, 48
	global_load_dwordx4 v[138:141], v[130:131], off
	v_or_b32_e32 v130, s14, v206
	v_or_b32_e32 v142, s14, v207
	v_ashrrev_i32_e32 v131, 31, v130
	v_ashrrev_i32_e32 v143, 31, v142
	v_lshlrev_b64 v[184:185], 11, v[130:131]
	v_lshlrev_b64 v[190:191], 11, v[142:143]
	v_lshl_add_u64 v[130:131], v[182:183], 0, v[184:185]
	v_lshl_add_u64 v[142:143], v[182:183], 0, v[190:191]
	global_load_dwordx4 v[130:133], v[130:131], off
	s_nop 0
	global_load_dwordx4 v[142:145], v[142:143], off
	s_waitcnt vmcnt(0)
	ds_write_b128 v209, v[154:157]
	ds_write_b128 v209, v[160:163] offset:1152
	ds_read_b128 v[154:157], v210
	s_waitcnt lgkmcnt(0)
	v_lshlrev_b32_e32 v160, 16, v154
	v_and_b32_e32 v154, 0xffff0000, v154
	v_add_f32_e32 v127, v127, v154
	v_lshlrev_b32_e32 v154, 16, v155
	v_add_f32_e32 v128, v128, v154
	v_and_b32_e32 v154, 0xffff0000, v155
	v_add_f32_e32 v129, v129, v154
	v_lshlrev_b32_e32 v154, 16, v156
	v_add_f32_e32 v154, v122, v154
	v_and_b32_e32 v122, 0xffff0000, v156
	v_add_f32_e32 v155, v123, v122
	v_lshlrev_b32_e32 v122, 16, v157
	v_add_f32_e32 v156, v124, v122
	v_and_b32_e32 v122, 0xffff0000, v157
	v_add_f32_e32 v126, v126, v160
	v_add_f32_e32 v157, v125, v122
	v_cvt_pk_bf16_f32 v122, v126, v127
	v_cvt_pk_bf16_f32 v123, v128, v129
	v_cvt_pk_bf16_f32 v124, v154, v155
	v_cvt_pk_bf16_f32 v125, v156, v157
	ds_write_b128 v210, v[122:125]
	v_mul_f32_e32 v122, v127, v127
	v_mul_f32_e32 v123, v129, v129
	v_fmac_f32_e32 v122, v126, v126
	v_fmac_f32_e32 v123, v128, v128
	v_add_f32_e32 v122, v122, v123
	v_mul_f32_e32 v123, v155, v155
	v_mul_f32_e32 v124, v157, v157
	v_fmac_f32_e32 v123, v154, v154
	v_fmac_f32_e32 v124, v156, v156
	v_add_f32_e32 v123, v123, v124
	v_add_f32_e32 v126, v122, v123
	ds_read_b128 v[122:125], v210 offset:64
	s_waitcnt lgkmcnt(0)
	v_lshlrev_b32_e32 v127, 16, v122
	v_and_b32_e32 v122, 0xffff0000, v122
	v_add_f32_e32 v119, v119, v122
	v_lshlrev_b32_e32 v122, 16, v123
	v_add_f32_e32 v120, v120, v122
	v_and_b32_e32 v122, 0xffff0000, v123
	v_add_f32_e32 v121, v121, v122
	v_lshlrev_b32_e32 v122, 16, v124
	v_add_f32_e32 v122, v114, v122
	v_and_b32_e32 v114, 0xffff0000, v124
	v_add_f32_e32 v123, v115, v114
	v_lshlrev_b32_e32 v114, 16, v125
	v_add_f32_e32 v124, v116, v114
	v_and_b32_e32 v114, 0xffff0000, v125
	v_add_f32_e32 v118, v118, v127
	v_add_f32_e32 v125, v117, v114
	v_cvt_pk_bf16_f32 v114, v118, v119
	v_cvt_pk_bf16_f32 v115, v120, v121
	v_cvt_pk_bf16_f32 v116, v122, v123
	v_cvt_pk_bf16_f32 v117, v124, v125
	ds_write_b128 v210, v[114:117] offset:64
	v_mul_f32_e32 v114, v119, v119
	v_mul_f32_e32 v115, v121, v121
	v_fmac_f32_e32 v114, v118, v118
	v_fmac_f32_e32 v115, v120, v120
	v_add_f32_e32 v114, v114, v115
	v_mul_f32_e32 v115, v123, v123
	v_mul_f32_e32 v116, v125, v125
	v_fmac_f32_e32 v115, v122, v122
	v_fmac_f32_e32 v116, v124, v124
	v_add_f32_e32 v115, v115, v116
	v_add_f32_e32 v114, v114, v115
	v_add_f32_e32 v120, v126, v114
	ds_read_b128 v[114:117], v211
	v_lshl_add_u64 v[118:119], s[76:77], 0, v[198:199]
	v_lshl_add_u64 v[118:119], v[118:119], 0, s[46:47]
	v_lshl_add_u64 v[118:119], v[118:119], 0, v[0:1]
	s_waitcnt lgkmcnt(0)
	global_store_dwordx4 v[118:119], v[114:117], off nt
	ds_read_b128 v[114:117], v211 offset:1152
	v_lshl_add_u64 v[118:119], s[76:77], 0, v[196:197]
	v_lshl_add_u64 v[118:119], v[118:119], 0, s[46:47]
	v_lshl_add_u64 v[118:119], v[118:119], 0, v[0:1]
	s_waitcnt lgkmcnt(0)
	global_store_dwordx4 v[118:119], v[114:117], off nt
	s_nop 1
	v_mov_b32_e32 v114, v120
	s_nop 1
	v_permlane16_swap_b32_e32 v120, v114
	v_add_f32_e32 v114, v120, v114
	v_mov_b32_e32 v115, v114
	s_nop 1
	v_permlane32_swap_b32_e32 v114, v115
	v_add_f32_e32 v164, v114, v115
	ds_write_b128 v209, v[146:149]
	ds_write_b128 v209, v[150:153] offset:1152
	ds_read_b128 v[114:117], v210
	s_waitcnt lgkmcnt(0)
; #define PG8_LAS __attribute__((address_space(3)))
; __device__ __forceinline__ unsigned cvt_pk_bf16(float lo, float hi) { unsigned r; asm volatile("v_cvt_pk_bf16_f32 %0, %1, %2" : "=v"(r) : "v"(lo), "v"(hi)); return r; }
; __device__ __forceinline__ float sum_x16(float s) { auto r = __builtin_amdgcn_permlane16_swap(__float_as_uint(s), __float_as_uint(s), false, false); return __uint_as_float(r[0]) + __uint_as_float(r[1]); }
; __device__ __forceinline__ float sum_x32(float s) { auto r = __builtin_amdgcn_permlane32_swap(__float_as_uint(s), __float_as_uint(s), false, false); return __uint_as_float(r[0]) + __uint_as_float(r[1]); }
;     __device__ __forceinline__ void operator()(const f32x4 (&acc)[2][2][4][2], const Unit& u, int wr, int wc, int fr, int fq, PG8_LAS unsigned char* stg) const {
;     ...
;         for (int m = 0; m < 4; ++m) {
;             const int row = rowb + ai * HALF + m * 16 + fr;
; #pragma unroll
;             for (int i = 0; i < 2; ++i) { const int c = lane + 64 * i; *(PG8_LAS u32x4*)(stg + (c >> 3) * 144 + (c & 7) * 16) = xin[m][i]; }
;             float ss = 0.f;
; #pragma unroll
;             for (int bj = 0; bj < 2; ++bj) {
;                 const u32x4 xo = *(const PG8_LAS u32x4*)(st + bj * 64);
;                 float v[8];
; #pragma unroll
;                 for (int i = 0; i < 4; ++i) { v[2 * i] = __uint_as_float(xo[i] << 16) + acc[ai][bj][m][i >> 1][(2 * i) & 3]; v[2 * i + 1] = __uint_as_float(xo[i] & 0xffff0000u) + acc[ai][bj][m][i >> 1][(2 * i + 1) & 3]; }
;                 u32x4 w; w.x = cvt_pk_bf16(v[0], v[1]); w.y = cvt_pk_bf16(v[2], v[3]); w.z = cvt_pk_bf16(v[4], v[5]); w.w = cvt_pk_bf16(v[6], v[7]);
;                 *(PG8_LAS u32x4*)(st + bj * 64) = w;
;                 ss += ((v[0] * v[0] + v[1] * v[1]) + (v[2] * v[2] + v[3] * v[3])) + ((v[4] * v[4] + v[5] * v[5]) + (v[6] * v[6] + v[7] * v[7]));
;             }
; #pragma unroll
;             for (int i = 0; i < 2; ++i) { const int c = lane + 64 * i; const u32x4 w = *(const PG8_LAS u32x4*)(stg + (c >> 3) * 144 + (c & 7) * 16);
;                 *(u32x4*)(xo_ + (size_t)(row - fr + (c >> 3)) * 1024 + colw + (c & 7) * 8) = w; }
;             ss = sum_x16(ss); ss = sum_x32(ss);
;             if (fq == 0) po_[(size_t)(u.pn * 4 + wc) * 65536 + row] = ss;
	v_lshlrev_b32_e32 v118, 16, v114
	v_and_b32_e32 v114, 0xffff0000, v114
	v_add_f32_e32 v111, v111, v114
	v_and_b32_e32 v114, 0xffff0000, v115
	v_add_f32_e32 v113, v113, v114
	v_lshlrev_b32_e32 v114, 16, v116
	v_add_f32_e32 v114, v106, v114
	v_and_b32_e32 v106, 0xffff0000, v116
	v_lshlrev_b32_e32 v119, 16, v115
	v_add_f32_e32 v115, v107, v106
	v_lshlrev_b32_e32 v106, 16, v117
	v_add_f32_e32 v116, v108, v106
	v_and_b32_e32 v106, 0xffff0000, v117
	v_add_f32_e32 v110, v110, v118
	v_add_f32_e32 v112, v112, v119
	v_add_f32_e32 v117, v109, v106
	v_cvt_pk_bf16_f32 v106, v110, v111
	v_cvt_pk_bf16_f32 v107, v112, v113
	v_cvt_pk_bf16_f32 v108, v114, v115
	v_cvt_pk_bf16_f32 v109, v116, v117
	ds_write_b128 v210, v[106:109]
	v_mul_f32_e32 v106, v111, v111
	v_mul_f32_e32 v107, v113, v113
	v_fmac_f32_e32 v106, v110, v110
	v_fmac_f32_e32 v107, v112, v112
	v_add_f32_e32 v110, v106, v107
	ds_read_b128 v[106:109], v210 offset:64
	v_mul_f32_e32 v111, v115, v115
	v_mul_f32_e32 v112, v117, v117
	v_fmac_f32_e32 v111, v114, v114
	v_fmac_f32_e32 v112, v116, v116
	v_add_f32_e32 v111, v111, v112
	v_add_f32_e32 v110, v110, v111
	s_waitcnt lgkmcnt(0)
	v_lshlrev_b32_e32 v111, 16, v106
	v_and_b32_e32 v106, 0xffff0000, v106
	v_add_f32_e32 v103, v103, v106
	v_lshlrev_b32_e32 v106, 16, v107
	v_add_f32_e32 v104, v104, v106
	v_and_b32_e32 v106, 0xffff0000, v107
	v_add_f32_e32 v105, v105, v106
	v_lshlrev_b32_e32 v106, 16, v108
	v_add_f32_e32 v106, v98, v106
	v_and_b32_e32 v98, 0xffff0000, v108
	v_add_f32_e32 v107, v99, v98
	v_lshlrev_b32_e32 v98, 16, v109
	v_add_f32_e32 v108, v100, v98
	v_and_b32_e32 v98, 0xffff0000, v109
	v_add_f32_e32 v102, v102, v111
	v_add_f32_e32 v109, v101, v98
	v_cvt_pk_bf16_f32 v98, v102, v103
	v_cvt_pk_bf16_f32 v99, v104, v105
	v_cvt_pk_bf16_f32 v100, v106, v107
	v_cvt_pk_bf16_f32 v101, v108, v109
	ds_write_b128 v210, v[98:101] offset:64
	v_mul_f32_e32 v98, v103, v103
	v_mul_f32_e32 v99, v105, v105
	v_fmac_f32_e32 v98, v102, v102
	v_fmac_f32_e32 v99, v104, v104
	v_add_f32_e32 v98, v98, v99
	v_mul_f32_e32 v99, v107, v107
	v_mul_f32_e32 v100, v109, v109
	v_fmac_f32_e32 v99, v106, v106
	v_fmac_f32_e32 v100, v108, v108
	v_add_f32_e32 v99, v99, v100
	v_add_f32_e32 v98, v98, v99
	v_add_f32_e32 v108, v110, v98
	ds_read_b128 v[98:101], v211
	v_lshl_add_u64 v[102:103], s[76:77], 0, v[194:195]
	v_lshl_add_u64 v[102:103], v[102:103], 0, s[46:47]
	v_lshl_add_u64 v[106:107], v[102:103], 0, v[0:1]
	ds_read_b128 v[102:105], v211 offset:1152
	s_waitcnt lgkmcnt(1)
	global_store_dwordx4 v[106:107], v[98:101], off nt
	s_nop 1
	v_lshl_add_u64 v[98:99], s[76:77], 0, v[192:193]
	v_lshl_add_u64 v[98:99], v[98:99], 0, s[46:47]
	v_lshl_add_u64 v[98:99], v[98:99], 0, v[0:1]
	s_waitcnt lgkmcnt(0)
	global_store_dwordx4 v[98:99], v[102:105], off nt
	v_mov_b32_e32 v98, v108
	s_nop 1
	v_permlane16_swap_b32_e32 v108, v98
	v_add_f32_e32 v98, v108, v98
	v_mov_b32_e32 v99, v98
	s_nop 1
	v_permlane32_swap_b32_e32 v98, v99
	v_add_f32_e32 v165, v98, v99
	ds_write_b128 v209, v[134:137]
	ds_write_b128 v209, v[138:141] offset:1152
	ds_read_b128 v[98:101], v210
	s_waitcnt lgkmcnt(0)
	v_lshlrev_b32_e32 v102, 16, v98
	v_and_b32_e32 v98, 0xffff0000, v98
	v_add_f32_e32 v95, v95, v98
	v_and_b32_e32 v98, 0xffff0000, v99
	v_add_f32_e32 v97, v97, v98
	v_lshlrev_b32_e32 v98, 16, v100
	v_add_f32_e32 v98, v90, v98
	v_and_b32_e32 v90, 0xffff0000, v100
	v_lshlrev_b32_e32 v103, 16, v99
	v_add_f32_e32 v99, v91, v90
	v_lshlrev_b32_e32 v90, 16, v101
	v_add_f32_e32 v100, v92, v90
	v_and_b32_e32 v90, 0xffff0000, v101
	v_add_f32_e32 v94, v94, v102
	v_add_f32_e32 v96, v96, v103
	v_add_f32_e32 v101, v93, v90
	v_cvt_pk_bf16_f32 v90, v94, v95
	v_cvt_pk_bf16_f32 v91, v96, v97
	v_cvt_pk_bf16_f32 v92, v98, v99
	v_cvt_pk_bf16_f32 v93, v100, v101
	ds_write_b128 v210, v[90:93]
	v_mul_f32_e32 v90, v95, v95
	v_mul_f32_e32 v91, v97, v97
	v_fmac_f32_e32 v90, v94, v94
	v_fmac_f32_e32 v91, v96, v96
	v_add_f32_e32 v94, v90, v91
	ds_read_b128 v[90:93], v210 offset:64
	v_mul_f32_e32 v95, v99, v99
	v_mul_f32_e32 v96, v101, v101
	v_fmac_f32_e32 v95, v98, v98
	v_fmac_f32_e32 v96, v100, v100
	v_add_f32_e32 v95, v95, v96
	v_add_f32_e32 v94, v94, v95
	s_waitcnt lgkmcnt(0)
	v_lshlrev_b32_e32 v95, 16, v90
	v_and_b32_e32 v90, 0xffff0000, v90
	v_add_f32_e32 v87, v87, v90
	v_lshlrev_b32_e32 v90, 16, v91
	v_add_f32_e32 v88, v88, v90
	v_and_b32_e32 v90, 0xffff0000, v91
	v_add_f32_e32 v89, v89, v90
	v_lshlrev_b32_e32 v90, 16, v92
	v_add_f32_e32 v90, v82, v90
	v_and_b32_e32 v82, 0xffff0000, v92
	v_add_f32_e32 v91, v83, v82
	v_lshlrev_b32_e32 v82, 16, v93
	v_add_f32_e32 v92, v84, v82
	v_and_b32_e32 v82, 0xffff0000, v93
	v_add_f32_e32 v86, v86, v95
	v_add_f32_e32 v93, v85, v82
	v_cvt_pk_bf16_f32 v82, v86, v87
	v_cvt_pk_bf16_f32 v83, v88, v89
	v_cvt_pk_bf16_f32 v84, v90, v91
	v_cvt_pk_bf16_f32 v85, v92, v93
	ds_write_b128 v210, v[82:85] offset:64
	v_mul_f32_e32 v82, v87, v87
	v_mul_f32_e32 v83, v89, v89
	v_fmac_f32_e32 v82, v86, v86
	v_fmac_f32_e32 v83, v88, v88
	v_add_f32_e32 v82, v82, v83
	v_mul_f32_e32 v83, v91, v91
	v_mul_f32_e32 v84, v93, v93
	v_fmac_f32_e32 v83, v90, v90
	v_fmac_f32_e32 v84, v92, v92
	v_add_f32_e32 v83, v83, v84
	v_add_f32_e32 v82, v82, v83
	v_add_f32_e32 v92, v94, v82
	ds_read_b128 v[82:85], v211
	v_lshl_add_u64 v[86:87], s[76:77], 0, v[188:189]
	v_lshl_add_u64 v[86:87], v[86:87], 0, s[46:47]
	v_lshl_add_u64 v[90:91], v[86:87], 0, v[0:1]
	ds_read_b128 v[86:89], v211 offset:1152
	s_waitcnt lgkmcnt(1)
	global_store_dwordx4 v[90:91], v[82:85], off nt
	s_nop 1
	v_lshl_add_u64 v[82:83], s[76:77], 0, v[186:187]
	v_lshl_add_u64 v[82:83], v[82:83], 0, s[46:47]
	v_lshl_add_u64 v[82:83], v[82:83], 0, v[0:1]
	s_waitcnt lgkmcnt(0)
; #define PG8_LAS __attribute__((address_space(3)))
; __device__ __forceinline__ unsigned cvt_pk_bf16(float lo, float hi) { unsigned r; asm volatile("v_cvt_pk_bf16_f32 %0, %1, %2" : "=v"(r) : "v"(lo), "v"(hi)); return r; }
; __device__ __forceinline__ float sum_x16(float s) { auto r = __builtin_amdgcn_permlane16_swap(__float_as_uint(s), __float_as_uint(s), false, false); return __uint_as_float(r[0]) + __uint_as_float(r[1]); }
; __device__ __forceinline__ float sum_x32(float s) { auto r = __builtin_amdgcn_permlane32_swap(__float_as_uint(s), __float_as_uint(s), false, false); return __uint_as_float(r[0]) + __uint_as_float(r[1]); }
;     __device__ __forceinline__ void operator()(const f32x4 (&acc)[2][2][4][2], const Unit& u, int wr, int wc, int fr, int fq, PG8_LAS unsigned char* stg) const {
;     ...
;         for (int m = 0; m < 4; ++m) {
;             const int row = rowb + ai * HALF + m * 16 + fr;
; #pragma unroll
;             for (int i = 0; i < 2; ++i) { const int c = lane + 64 * i; *(PG8_LAS u32x4*)(stg + (c >> 3) * 144 + (c & 7) * 16) = xin[m][i]; }
;             float ss = 0.f;
; #pragma unroll
;             for (int bj = 0; bj < 2; ++bj) {
;                 const u32x4 xo = *(const PG8_LAS u32x4*)(st + bj * 64);
;                 float v[8];
; #pragma unroll
;                 for (int i = 0; i < 4; ++i) { v[2 * i] = __uint_as_float(xo[i] << 16) + acc[ai][bj][m][i >> 1][(2 * i) & 3]; v[2 * i + 1] = __uint_as_float(xo[i] & 0xffff0000u) + acc[ai][bj][m][i >> 1][(2 * i + 1) & 3]; }
;                 u32x4 w; w.x = cvt_pk_bf16(v[0], v[1]); w.y = cvt_pk_bf16(v[2], v[3]); w.z = cvt_pk_bf16(v[4], v[5]); w.w = cvt_pk_bf16(v[6], v[7]);
;                 *(PG8_LAS u32x4*)(st + bj * 64) = w;
;                 ss += ((v[0] * v[0] + v[1] * v[1]) + (v[2] * v[2] + v[3] * v[3])) + ((v[4] * v[4] + v[5] * v[5]) + (v[6] * v[6] + v[7] * v[7]));
;             }
; #pragma unroll
;             for (int i = 0; i < 2; ++i) { const int c = lane + 64 * i; const u32x4 w = *(const PG8_LAS u32x4*)(stg + (c >> 3) * 144 + (c & 7) * 16);
;                 *(u32x4*)(xo_ + (size_t)(row - fr + (c >> 3)) * 1024 + colw + (c & 7) * 8) = w; }
;             ss = sum_x16(ss); ss = sum_x32(ss);
;             if (fq == 0) po_[(size_t)(u.pn * 4 + wc) * 65536 + row] = ss;
	global_store_dwordx4 v[82:83], v[86:89], off nt
	v_mov_b32_e32 v82, v92
	s_nop 1
	v_permlane16_swap_b32_e32 v92, v82
	v_add_f32_e32 v82, v92, v82
	v_mov_b32_e32 v83, v82
	s_nop 1
	v_permlane32_swap_b32_e32 v82, v83
	v_add_f32_e32 v166, v82, v83
	ds_write_b128 v209, v[130:133]
	ds_write_b128 v209, v[142:145] offset:1152
	ds_read_b128 v[82:85], v210
	s_waitcnt lgkmcnt(0)
	v_lshlrev_b32_e32 v86, 16, v82
	v_and_b32_e32 v82, 0xffff0000, v82
	v_add_f32_e32 v79, v79, v82
	v_and_b32_e32 v82, 0xffff0000, v83
	v_add_f32_e32 v81, v81, v82
	v_lshlrev_b32_e32 v82, 16, v84
	v_add_f32_e32 v82, v74, v82
	v_and_b32_e32 v74, 0xffff0000, v84
	v_lshlrev_b32_e32 v87, 16, v83
	v_add_f32_e32 v83, v75, v74
	v_lshlrev_b32_e32 v74, 16, v85
	v_add_f32_e32 v84, v76, v74
	v_and_b32_e32 v74, 0xffff0000, v85
	v_add_f32_e32 v78, v78, v86
	v_add_f32_e32 v80, v80, v87
	v_add_f32_e32 v85, v77, v74
	v_cvt_pk_bf16_f32 v74, v78, v79
	v_cvt_pk_bf16_f32 v75, v80, v81
	v_cvt_pk_bf16_f32 v76, v82, v83
	v_cvt_pk_bf16_f32 v77, v84, v85
	ds_write_b128 v210, v[74:77]
	v_mul_f32_e32 v74, v79, v79
	v_mul_f32_e32 v75, v81, v81
	v_fmac_f32_e32 v74, v78, v78
	v_fmac_f32_e32 v75, v80, v80
	v_add_f32_e32 v78, v74, v75
	ds_read_b128 v[74:77], v210 offset:64
	v_mul_f32_e32 v79, v83, v83
	v_mul_f32_e32 v80, v85, v85
	v_fmac_f32_e32 v79, v82, v82
	v_fmac_f32_e32 v80, v84, v84
	v_add_f32_e32 v79, v79, v80
	v_add_f32_e32 v78, v78, v79
	s_waitcnt lgkmcnt(0)
	v_lshlrev_b32_e32 v79, 16, v74
	v_and_b32_e32 v74, 0xffff0000, v74
	v_add_f32_e32 v71, v71, v74
	v_lshlrev_b32_e32 v74, 16, v75
	v_add_f32_e32 v72, v72, v74
	v_and_b32_e32 v74, 0xffff0000, v75
	v_add_f32_e32 v73, v73, v74
	v_lshlrev_b32_e32 v74, 16, v76
	v_add_f32_e32 v74, v66, v74
	v_and_b32_e32 v66, 0xffff0000, v76
	v_add_f32_e32 v75, v67, v66
	v_lshlrev_b32_e32 v66, 16, v77
	v_add_f32_e32 v76, v68, v66
	v_and_b32_e32 v66, 0xffff0000, v77
	v_add_f32_e32 v70, v70, v79
	v_add_f32_e32 v77, v69, v66
	v_cvt_pk_bf16_f32 v66, v70, v71
	v_cvt_pk_bf16_f32 v67, v72, v73
	v_cvt_pk_bf16_f32 v68, v74, v75
	v_cvt_pk_bf16_f32 v69, v76, v77
	ds_write_b128 v210, v[66:69] offset:64
	v_mul_f32_e32 v66, v71, v71
	v_mul_f32_e32 v67, v73, v73
	v_fmac_f32_e32 v66, v70, v70
	v_fmac_f32_e32 v67, v72, v72
	v_add_f32_e32 v66, v66, v67
	v_mul_f32_e32 v67, v75, v75
	v_mul_f32_e32 v68, v77, v77
	v_fmac_f32_e32 v67, v74, v74
	v_fmac_f32_e32 v68, v76, v76
	v_add_f32_e32 v67, v67, v68
	v_add_f32_e32 v66, v66, v67
	v_add_f32_e32 v76, v78, v66
	ds_read_b128 v[66:69], v211
	v_lshl_add_u64 v[70:71], s[76:77], 0, v[184:185]
	v_lshl_add_u64 v[70:71], v[70:71], 0, s[46:47]
	v_lshl_add_u64 v[74:75], v[70:71], 0, v[0:1]
	ds_read_b128 v[70:73], v211 offset:1152
	s_waitcnt lgkmcnt(1)
	global_store_dwordx4 v[74:75], v[66:69], off nt
	s_nop 1
	v_lshl_add_u64 v[66:67], s[76:77], 0, v[190:191]
	v_lshl_add_u64 v[66:67], v[66:67], 0, s[46:47]
	v_lshl_add_u64 v[66:67], v[66:67], 0, v[0:1]
	s_waitcnt lgkmcnt(0)
	global_store_dwordx4 v[66:67], v[70:73], off nt
	v_mov_b32_e32 v66, v76
	s_nop 1
	v_permlane16_swap_b32_e32 v76, v66
	v_add_f32_e32 v66, v76, v66
	v_mov_b32_e32 v67, v66
	s_nop 1
	v_permlane32_swap_b32_e32 v66, v67
	v_add_f32_e32 v167, v66, v67
	v_mbcnt_lo_u32_b32 v200, -1, 0
	v_mbcnt_hi_u32_b32 v200, -1, v200
	v_lshrrev_b32_e32 v201, 4, v200
	v_cmp_eq_u32_e64 s[100:101], 1, v201
	s_nop 1
	v_cndmask_b32_e64 v212, v164, v165, s[100:101]
	v_cmp_eq_u32_e64 s[100:101], 2, v201
	s_nop 1
	v_cndmask_b32_e64 v212, v212, v166, s[100:101]
	v_cmp_eq_u32_e64 s[100:101], 3, v201
	s_nop 1
	v_cndmask_b32_e64 v212, v212, v167, s[100:101]
	s_nop 1
	s_add_u32 s100, s82, s44
	s_addc_u32 s101, s83, s45
	v_or_b32_e32 v201, s42, v174
	v_lshlrev_b32_e32 v201, 2, v201
	v_and_b32_e32 v200, 48, v200
	v_lshl_add_u32 v201, v200, 2, v201
	global_store_dword v201, v212, s[100:101] offset:0
	s_add_i32 s14, s42, 0x80
	v_or_b32_e32 v66, s14, v206
	v_ashrrev_i32_e32 v67, 31, v66
	v_lshlrev_b64 v[104:105], 11, v[66:67]
	v_lshl_add_u64 v[66:67], v[182:183], 0, v[104:105]
	global_load_dwordx4 v[106:109], v[66:67], off
	v_or_b32_e32 v66, s14, v207
	v_ashrrev_i32_e32 v67, 31, v66
	v_lshlrev_b64 v[102:103], 11, v[66:67]
	v_lshl_add_u64 v[66:67], v[182:183], 0, v[102:103]
	global_load_dwordx4 v[110:113], v[66:67], off
	s_add_i32 s14, s42, 0x90
	v_or_b32_e32 v66, s14, v206
	v_ashrrev_i32_e32 v67, 31, v66
	v_lshlrev_b64 v[100:101], 11, v[66:67]
	v_lshl_add_u64 v[66:67], v[182:183], 0, v[100:101]
	global_load_dwordx4 v[82:85], v[66:67], off
	v_or_b32_e32 v66, s14, v207
	v_ashrrev_i32_e32 v67, 31, v66
	v_lshlrev_b64 v[98:99], 11, v[66:67]
	v_lshl_add_u64 v[66:67], v[182:183], 0, v[98:99]
	s_add_i32 s14, s42, 0xa0
	global_load_dwordx4 v[86:89], v[66:67], off
	v_or_b32_e32 v66, s14, v206
	v_ashrrev_i32_e32 v67, 31, v66
	v_lshlrev_b64 v[94:95], 11, v[66:67]
	v_lshl_add_u64 v[66:67], v[182:183], 0, v[94:95]
	global_load_dwordx4 v[70:73], v[66:67], off
	v_or_b32_e32 v66, s14, v207
	v_ashrrev_i32_e32 v67, 31, v66
	v_lshlrev_b64 v[92:93], 11, v[66:67]
	v_lshl_add_u64 v[66:67], v[182:183], 0, v[92:93]
	s_add_i32 s14, s42, 0xb0
	global_load_dwordx4 v[74:77], v[66:67], off
	v_or_b32_e32 v66, s14, v206
	v_or_b32_e32 v78, s14, v207
	v_ashrrev_i32_e32 v67, 31, v66
	v_ashrrev_i32_e32 v79, 31, v78
	v_lshlrev_b64 v[90:91], 11, v[66:67]
	v_lshlrev_b64 v[96:97], 11, v[78:79]
	v_lshl_add_u64 v[66:67], v[182:183], 0, v[90:91]
	v_lshl_add_u64 v[78:79], v[182:183], 0, v[96:97]
	global_load_dwordx4 v[66:69], v[66:67], off
	s_nop 0
	global_load_dwordx4 v[78:81], v[78:79], off
	s_waitcnt vmcnt(7)
	ds_write_b128 v209, v[106:109]
	s_waitcnt vmcnt(6)
	ds_write_b128 v209, v[110:113] offset:1152
	ds_read_b128 v[106:109], v210
	s_waitcnt lgkmcnt(0)
; #define PG8_LAS __attribute__((address_space(3)))
; __device__ __forceinline__ unsigned cvt_pk_bf16(float lo, float hi) { unsigned r; asm volatile("v_cvt_pk_bf16_f32 %0, %1, %2" : "=v"(r) : "v"(lo), "v"(hi)); return r; }
; __device__ __forceinline__ float sum_x16(float s) { auto r = __builtin_amdgcn_permlane16_swap(__float_as_uint(s), __float_as_uint(s), false, false); return __uint_as_float(r[0]) + __uint_as_float(r[1]); }
; __device__ __forceinline__ float sum_x32(float s) { auto r = __builtin_amdgcn_permlane32_swap(__float_as_uint(s), __float_as_uint(s), false, false); return __uint_as_float(r[0]) + __uint_as_float(r[1]); }
;     __device__ __forceinline__ void operator()(const f32x4 (&acc)[2][2][4][2], const Unit& u, int wr, int wc, int fr, int fq, PG8_LAS unsigned char* stg) const {
;     ...
;         for (int m = 0; m < 4; ++m) {
;             const int row = rowb + ai * HALF + m * 16 + fr;
; #pragma unroll
;             for (int i = 0; i < 2; ++i) { const int c = lane + 64 * i; *(PG8_LAS u32x4*)(stg + (c >> 3) * 144 + (c & 7) * 16) = xin[m][i]; }
;             float ss = 0.f;
; #pragma unroll
;             for (int bj = 0; bj < 2; ++bj) {
;                 const u32x4 xo = *(const PG8_LAS u32x4*)(st + bj * 64);
;                 float v[8];
; #pragma unroll
;                 for (int i = 0; i < 4; ++i) { v[2 * i] = __uint_as_float(xo[i] << 16) + acc[ai][bj][m][i >> 1][(2 * i) & 3]; v[2 * i + 1] = __uint_as_float(xo[i] & 0xffff0000u) + acc[ai][bj][m][i >> 1][(2 * i + 1) & 3]; }
;                 u32x4 w; w.x = cvt_pk_bf16(v[0], v[1]); w.y = cvt_pk_bf16(v[2], v[3]); w.z = cvt_pk_bf16(v[4], v[5]); w.w = cvt_pk_bf16(v[6], v[7]);
;                 *(PG8_LAS u32x4*)(st + bj * 64) = w;
;                 ss += ((v[0] * v[0] + v[1] * v[1]) + (v[2] * v[2] + v[3] * v[3])) + ((v[4] * v[4] + v[5] * v[5]) + (v[6] * v[6] + v[7] * v[7]));
;             }
; #pragma unroll
;             for (int i = 0; i < 2; ++i) { const int c = lane + 64 * i; const u32x4 w = *(const PG8_LAS u32x4*)(stg + (c >> 3) * 144 + (c & 7) * 16);
;                 *(u32x4*)(xo_ + (size_t)(row - fr + (c >> 3)) * 1024 + colw + (c & 7) * 8) = w; }
;             ss = sum_x16(ss); ss = sum_x32(ss);
;             if (fq == 0) po_[(size_t)(u.pn * 4 + wc) * 65536 + row] = ss;
	v_lshlrev_b32_e32 v110, 16, v106
	v_and_b32_e32 v106, 0xffff0000, v106
	v_add_f32_e32 v63, v63, v106
	v_lshlrev_b32_e32 v106, 16, v107
	v_add_f32_e32 v64, v64, v106
	v_and_b32_e32 v106, 0xffff0000, v107
	v_add_f32_e32 v65, v65, v106
	v_lshlrev_b32_e32 v106, 16, v108
	v_add_f32_e32 v106, v58, v106
	v_and_b32_e32 v58, 0xffff0000, v108
	v_add_f32_e32 v107, v59, v58
	v_lshlrev_b32_e32 v58, 16, v109
	v_add_f32_e32 v108, v60, v58
	v_and_b32_e32 v58, 0xffff0000, v109
	v_add_f32_e32 v62, v62, v110
	v_add_f32_e32 v109, v61, v58
	v_cvt_pk_bf16_f32 v58, v62, v63
	v_cvt_pk_bf16_f32 v59, v64, v65
	v_cvt_pk_bf16_f32 v60, v106, v107
	v_cvt_pk_bf16_f32 v61, v108, v109
	ds_write_b128 v210, v[58:61]
	v_mul_f32_e32 v58, v63, v63
	v_mul_f32_e32 v59, v65, v65
	v_fmac_f32_e32 v58, v62, v62
	v_fmac_f32_e32 v59, v64, v64
	v_add_f32_e32 v58, v58, v59
	v_mul_f32_e32 v59, v107, v107
	v_mul_f32_e32 v60, v109, v109
	v_fmac_f32_e32 v59, v106, v106
	v_fmac_f32_e32 v60, v108, v108
	v_add_f32_e32 v59, v59, v60
	v_add_f32_e32 v62, v58, v59
	ds_read_b128 v[58:61], v210 offset:64
	s_waitcnt lgkmcnt(0)
	v_lshlrev_b32_e32 v63, 16, v58
	v_and_b32_e32 v58, 0xffff0000, v58
	v_add_f32_e32 v55, v55, v58
	v_lshlrev_b32_e32 v58, 16, v59
	v_add_f32_e32 v56, v56, v58
	v_and_b32_e32 v58, 0xffff0000, v59
	v_add_f32_e32 v57, v57, v58
	v_lshlrev_b32_e32 v58, 16, v60
	v_add_f32_e32 v58, v50, v58
	v_and_b32_e32 v50, 0xffff0000, v60
	v_add_f32_e32 v59, v51, v50
	v_lshlrev_b32_e32 v50, 16, v61
	v_add_f32_e32 v60, v52, v50
	v_and_b32_e32 v50, 0xffff0000, v61
	v_add_f32_e32 v54, v54, v63
	v_add_f32_e32 v61, v53, v50
	v_cvt_pk_bf16_f32 v50, v54, v55
	v_cvt_pk_bf16_f32 v51, v56, v57
	v_cvt_pk_bf16_f32 v52, v58, v59
	v_cvt_pk_bf16_f32 v53, v60, v61
	ds_write_b128 v210, v[50:53] offset:64
	v_mul_f32_e32 v50, v55, v55
	v_mul_f32_e32 v51, v57, v57
	v_fmac_f32_e32 v50, v54, v54
	v_fmac_f32_e32 v51, v56, v56
	v_add_f32_e32 v50, v50, v51
	v_mul_f32_e32 v51, v59, v59
	v_mul_f32_e32 v52, v61, v61
	v_fmac_f32_e32 v51, v58, v58
	v_fmac_f32_e32 v52, v60, v60
	v_add_f32_e32 v51, v51, v52
	v_add_f32_e32 v50, v50, v51
	v_add_f32_e32 v56, v62, v50
	ds_read_b128 v[50:53], v211
	v_lshl_add_u64 v[54:55], s[76:77], 0, v[104:105]
	v_lshl_add_u64 v[54:55], v[54:55], 0, s[46:47]
	v_lshl_add_u64 v[54:55], v[54:55], 0, v[0:1]
	s_waitcnt lgkmcnt(0)
	global_store_dwordx4 v[54:55], v[50:53], off nt
	ds_read_b128 v[50:53], v211 offset:1152
	v_lshl_add_u64 v[54:55], s[76:77], 0, v[102:103]
	v_lshl_add_u64 v[54:55], v[54:55], 0, s[46:47]
	v_lshl_add_u64 v[54:55], v[54:55], 0, v[0:1]
	s_waitcnt lgkmcnt(0)
	global_store_dwordx4 v[54:55], v[50:53], off nt
	s_nop 1
	v_mov_b32_e32 v50, v56
	s_nop 1
	v_permlane16_swap_b32_e32 v56, v50
	v_add_f32_e32 v50, v56, v50
	v_mov_b32_e32 v51, v50
	s_nop 1
	v_permlane32_swap_b32_e32 v50, v51
	v_add_f32_e32 v164, v50, v51
	s_waitcnt vmcnt(7)
	ds_write_b128 v209, v[82:85]
	s_waitcnt vmcnt(6)
	ds_write_b128 v209, v[86:89] offset:1152
	ds_read_b128 v[50:53], v210
	s_waitcnt lgkmcnt(0)
	v_lshlrev_b32_e32 v54, 16, v50
	v_and_b32_e32 v50, 0xffff0000, v50
	v_add_f32_e32 v47, v47, v50
	v_and_b32_e32 v50, 0xffff0000, v51
	v_add_f32_e32 v49, v49, v50
	v_lshlrev_b32_e32 v50, 16, v52
	v_add_f32_e32 v50, v42, v50
	v_and_b32_e32 v42, 0xffff0000, v52
	v_lshlrev_b32_e32 v55, 16, v51
	v_add_f32_e32 v51, v43, v42
	v_lshlrev_b32_e32 v42, 16, v53
	v_add_f32_e32 v52, v44, v42
	v_and_b32_e32 v42, 0xffff0000, v53
	v_add_f32_e32 v46, v46, v54
	v_add_f32_e32 v48, v48, v55
	v_add_f32_e32 v53, v45, v42
	v_cvt_pk_bf16_f32 v42, v46, v47
	v_cvt_pk_bf16_f32 v43, v48, v49
	v_cvt_pk_bf16_f32 v44, v50, v51
	v_cvt_pk_bf16_f32 v45, v52, v53
	ds_write_b128 v210, v[42:45]
	v_mul_f32_e32 v42, v47, v47
	v_mul_f32_e32 v43, v49, v49
	v_fmac_f32_e32 v42, v46, v46
	v_fmac_f32_e32 v43, v48, v48
	v_add_f32_e32 v46, v42, v43
	ds_read_b128 v[42:45], v210 offset:64
	v_mul_f32_e32 v47, v51, v51
	v_mul_f32_e32 v48, v53, v53
	v_fmac_f32_e32 v47, v50, v50
	v_fmac_f32_e32 v48, v52, v52
	v_add_f32_e32 v47, v47, v48
	v_add_f32_e32 v46, v46, v47
	s_waitcnt lgkmcnt(0)
	v_lshlrev_b32_e32 v47, 16, v42
	v_and_b32_e32 v42, 0xffff0000, v42
	v_add_f32_e32 v39, v39, v42
	v_lshlrev_b32_e32 v42, 16, v43
	v_add_f32_e32 v40, v40, v42
	v_and_b32_e32 v42, 0xffff0000, v43
	v_add_f32_e32 v41, v41, v42
	v_lshlrev_b32_e32 v42, 16, v44
	v_add_f32_e32 v42, v34, v42
	v_and_b32_e32 v34, 0xffff0000, v44
	v_add_f32_e32 v43, v35, v34
	v_lshlrev_b32_e32 v34, 16, v45
	v_add_f32_e32 v44, v36, v34
	v_and_b32_e32 v34, 0xffff0000, v45
	v_add_f32_e32 v38, v38, v47
	v_add_f32_e32 v45, v37, v34
	v_cvt_pk_bf16_f32 v34, v38, v39
	v_cvt_pk_bf16_f32 v35, v40, v41
	v_cvt_pk_bf16_f32 v36, v42, v43
	v_cvt_pk_bf16_f32 v37, v44, v45
	ds_write_b128 v210, v[34:37] offset:64
	v_mul_f32_e32 v34, v39, v39
	v_mul_f32_e32 v35, v41, v41
	v_fmac_f32_e32 v34, v38, v38
	v_fmac_f32_e32 v35, v40, v40
	v_add_f32_e32 v34, v34, v35
	v_mul_f32_e32 v35, v43, v43
	v_mul_f32_e32 v36, v45, v45
	v_fmac_f32_e32 v35, v42, v42
	v_fmac_f32_e32 v36, v44, v44
	v_add_f32_e32 v35, v35, v36
	v_add_f32_e32 v34, v34, v35
	v_add_f32_e32 v44, v46, v34
	ds_read_b128 v[34:37], v211
	v_lshl_add_u64 v[38:39], s[76:77], 0, v[100:101]
	v_lshl_add_u64 v[38:39], v[38:39], 0, s[46:47]
	v_lshl_add_u64 v[42:43], v[38:39], 0, v[0:1]
	ds_read_b128 v[38:41], v211 offset:1152
	s_waitcnt lgkmcnt(1)
	global_store_dwordx4 v[42:43], v[34:37], off nt
	s_nop 1
	v_lshl_add_u64 v[34:35], s[76:77], 0, v[98:99]
	v_lshl_add_u64 v[34:35], v[34:35], 0, s[46:47]
	v_lshl_add_u64 v[34:35], v[34:35], 0, v[0:1]
	s_waitcnt lgkmcnt(0)
; #define PG8_LAS __attribute__((address_space(3)))
;     __device__ __forceinline__ void operator()(const f32x4 (&acc)[2][2][4][2], const Unit& u, int wr, int wc, int fr, int fq, PG8_LAS unsigned char* stg) const {
;     ...
;         for (int m = 0; m < 4; ++m) {
;             const int row = rowb + ai * HALF + m * 16 + fr;
; #pragma unroll
;             for (int i = 0; i < 2; ++i) { const int c = lane + 64 * i; *(PG8_LAS u32x4*)(stg + (c >> 3) * 144 + (c & 7) * 16) = xin[m][i]; }
;             float ss = 0.f;
; #pragma unroll
;             for (int bj = 0; bj < 2; ++bj) {
;                 const u32x4 xo = *(const PG8_LAS u32x4*)(st + bj * 64);
;                 float v[8];
; #pragma unroll
;                 for (int i = 0; i < 4; ++i) { v[2 * i] = __uint_as_float(xo[i] << 16) + acc[ai][bj][m][i >> 1][(2 * i) & 3]; v[2 * i + 1] = __uint_as_float(xo[i] & 0xffff0000u) + acc[ai][bj][m][i >> 1][(2 * i + 1) & 3]; }
;                 u32x4 w; w.x = cvt_pk_bf16(v[0], v[1]); w.y = cvt_pk_bf16(v[2], v[3]); w.z = cvt_pk_bf16(v[4], v[5]); w.w = cvt_pk_bf16(v[6], v[7]);
;                 *(PG8_LAS u32x4*)(st + bj * 64) = w;
;                 ss += ((v[0] * v[0] + v[1] * v[1]) + (v[2] * v[2] + v[3] * v[3])) + ((v[4] * v[4] + v[5] * v[5]) + (v[6] * v[6] + v[7] * v[7]));
;             }
; #pragma unroll
;             for (int i = 0; i < 2; ++i) { const int c = lane + 64 * i; const u32x4 w = *(const PG8_LAS u32x4*)(stg + (c >> 3) * 144 + (c & 7) * 16);
;                 *(u32x4*)(xo_ + (size_t)(row - fr + (c >> 3)) * 1024 + colw + (c & 7) * 8) = w; }
;             ss = sum_x16(ss); ss = sum_x32(ss);
;             if (fq == 0) po_[(size_t)(u.pn * 4 + wc) * 65536 + row] = ss;
; template <class Epi, class Sched, bool ALIGN_EPI = false, bool SP2 = false>
; __device__ __forceinline__ void gemm_phase(PG8_LAS unsigned char* lds, const Gemm g, const Sched& S, const Epi& E, const int wave_s) {
;     ...
;         if (!has_next) break;
; #pragma unroll
;         for (int a = 0; a < 2; ++a)
; #pragma unroll
;             for (int b = 0; b < 2; ++b)
; #pragma unroll
;                 for (int m = 0; m < 4; ++m)
; #pragma unroll
;                     for (int n = 0; n < 2; ++n) acc[a][b][m][n] = (f32x4){0.f, 0.f, 0.f, 0.f};
;         if (nxt.pm != cur.pm) rs_par ^= 1;
;         cur = nxt; cA = nA; cB = nB; ++ui;
;         if constexpr (ALIGN_EPI) { if (wr == 1) PG8_BAR; }
	global_store_dwordx4 v[34:35], v[38:41], off nt
	v_mov_b32_e32 v34, v44
	s_nop 1
	v_permlane16_swap_b32_e32 v44, v34
	v_add_f32_e32 v34, v44, v34
	v_mov_b32_e32 v35, v34
	s_nop 1
	v_permlane32_swap_b32_e32 v34, v35
	v_add_f32_e32 v165, v34, v35
	s_waitcnt vmcnt(7)
	ds_write_b128 v209, v[70:73]
	s_waitcnt vmcnt(6)
	ds_write_b128 v209, v[74:77] offset:1152
	ds_read_b128 v[34:37], v210
	s_waitcnt lgkmcnt(0)
	v_lshlrev_b32_e32 v38, 16, v34
	v_and_b32_e32 v34, 0xffff0000, v34
	v_add_f32_e32 v31, v31, v34
	v_and_b32_e32 v34, 0xffff0000, v35
	v_add_f32_e32 v33, v33, v34
	v_lshlrev_b32_e32 v34, 16, v36
	v_add_f32_e32 v34, v26, v34
	v_and_b32_e32 v26, 0xffff0000, v36
	v_lshlrev_b32_e32 v39, 16, v35
	v_add_f32_e32 v35, v27, v26
	v_lshlrev_b32_e32 v26, 16, v37
	v_add_f32_e32 v36, v28, v26
	v_and_b32_e32 v26, 0xffff0000, v37
	v_add_f32_e32 v30, v30, v38
	v_add_f32_e32 v32, v32, v39
	v_add_f32_e32 v37, v29, v26
	v_cvt_pk_bf16_f32 v26, v30, v31
	v_cvt_pk_bf16_f32 v27, v32, v33
	v_cvt_pk_bf16_f32 v28, v34, v35
	v_cvt_pk_bf16_f32 v29, v36, v37
	ds_write_b128 v210, v[26:29]
	v_mul_f32_e32 v26, v31, v31
	v_mul_f32_e32 v27, v33, v33
	v_fmac_f32_e32 v26, v30, v30
	v_fmac_f32_e32 v27, v32, v32
	v_add_f32_e32 v30, v26, v27
	ds_read_b128 v[26:29], v210 offset:64
	v_mul_f32_e32 v31, v35, v35
	v_mul_f32_e32 v32, v37, v37
	v_fmac_f32_e32 v31, v34, v34
	v_fmac_f32_e32 v32, v36, v36
	v_add_f32_e32 v31, v31, v32
	v_add_f32_e32 v30, v30, v31
	s_waitcnt lgkmcnt(0)
	v_lshlrev_b32_e32 v31, 16, v26
	v_and_b32_e32 v26, 0xffff0000, v26
	v_add_f32_e32 v23, v23, v26
	v_lshlrev_b32_e32 v26, 16, v27
	v_add_f32_e32 v24, v24, v26
	v_and_b32_e32 v26, 0xffff0000, v27
	v_add_f32_e32 v25, v25, v26
	v_lshlrev_b32_e32 v26, 16, v28
	v_add_f32_e32 v26, v18, v26
	v_and_b32_e32 v18, 0xffff0000, v28
	v_add_f32_e32 v27, v19, v18
	v_lshlrev_b32_e32 v18, 16, v29
	v_add_f32_e32 v28, v20, v18
	v_and_b32_e32 v18, 0xffff0000, v29
	v_add_f32_e32 v22, v22, v31
	v_add_f32_e32 v29, v21, v18
	v_cvt_pk_bf16_f32 v18, v22, v23
	v_cvt_pk_bf16_f32 v19, v24, v25
	v_cvt_pk_bf16_f32 v20, v26, v27
	v_cvt_pk_bf16_f32 v21, v28, v29
	ds_write_b128 v210, v[18:21] offset:64
	v_mul_f32_e32 v18, v23, v23
	v_mul_f32_e32 v19, v25, v25
	v_fmac_f32_e32 v18, v22, v22
	v_fmac_f32_e32 v19, v24, v24
	v_add_f32_e32 v18, v18, v19
	v_mul_f32_e32 v19, v27, v27
	v_mul_f32_e32 v20, v29, v29
	v_fmac_f32_e32 v19, v26, v26
	v_fmac_f32_e32 v20, v28, v28
	v_add_f32_e32 v19, v19, v20
	v_add_f32_e32 v18, v18, v19
	v_add_f32_e32 v28, v30, v18
	ds_read_b128 v[18:21], v211
	v_lshl_add_u64 v[22:23], s[76:77], 0, v[94:95]
	v_lshl_add_u64 v[22:23], v[22:23], 0, s[46:47]
	v_lshl_add_u64 v[26:27], v[22:23], 0, v[0:1]
	ds_read_b128 v[22:25], v211 offset:1152
	s_waitcnt lgkmcnt(1)
	global_store_dwordx4 v[26:27], v[18:21], off nt
	s_nop 1
	v_lshl_add_u64 v[18:19], s[76:77], 0, v[92:93]
	v_lshl_add_u64 v[18:19], v[18:19], 0, s[46:47]
	v_lshl_add_u64 v[18:19], v[18:19], 0, v[0:1]
	s_waitcnt lgkmcnt(0)
	global_store_dwordx4 v[18:19], v[22:25], off nt
	v_mov_b32_e32 v18, v28
	s_nop 1
	v_permlane16_swap_b32_e32 v28, v18
	v_add_f32_e32 v18, v28, v18
	v_mov_b32_e32 v19, v18
	s_nop 1
	v_permlane32_swap_b32_e32 v18, v19
	v_add_f32_e32 v166, v18, v19
	s_waitcnt vmcnt(7)
	ds_write_b128 v209, v[66:69]
	s_waitcnt vmcnt(6)
	ds_write_b128 v209, v[78:81] offset:1152
	ds_read_b128 v[18:21], v210
	s_waitcnt lgkmcnt(0)
	v_lshlrev_b32_e32 v22, 16, v18
	v_and_b32_e32 v18, 0xffff0000, v18
	v_add_f32_e32 v15, v15, v18
	v_and_b32_e32 v18, 0xffff0000, v19
	v_add_f32_e32 v17, v17, v18
	v_lshlrev_b32_e32 v18, 16, v20
	v_add_f32_e32 v18, v10, v18
	v_and_b32_e32 v10, 0xffff0000, v20
	v_lshlrev_b32_e32 v23, 16, v19
	v_add_f32_e32 v19, v11, v10
	v_lshlrev_b32_e32 v10, 16, v21
	v_add_f32_e32 v20, v12, v10
	v_and_b32_e32 v10, 0xffff0000, v21
	v_add_f32_e32 v14, v14, v22
	v_add_f32_e32 v16, v16, v23
	v_add_f32_e32 v21, v13, v10
	v_cvt_pk_bf16_f32 v10, v14, v15
	v_cvt_pk_bf16_f32 v11, v16, v17
	v_cvt_pk_bf16_f32 v12, v18, v19
	v_cvt_pk_bf16_f32 v13, v20, v21
	ds_write_b128 v210, v[10:13]
	v_mul_f32_e32 v10, v15, v15
	v_mul_f32_e32 v11, v17, v17
	v_fmac_f32_e32 v10, v14, v14
	v_fmac_f32_e32 v11, v16, v16
	v_add_f32_e32 v14, v10, v11
	ds_read_b128 v[10:13], v210 offset:64
	v_mul_f32_e32 v15, v19, v19
	v_mul_f32_e32 v16, v21, v21
	v_fmac_f32_e32 v15, v18, v18
	v_fmac_f32_e32 v16, v20, v20
	v_add_f32_e32 v15, v15, v16
	v_add_f32_e32 v14, v14, v15
	s_waitcnt lgkmcnt(0)
	v_lshlrev_b32_e32 v15, 16, v10
	v_and_b32_e32 v10, 0xffff0000, v10
	v_add_f32_e32 v7, v7, v10
	v_lshlrev_b32_e32 v10, 16, v11
	v_add_f32_e32 v8, v8, v10
	v_and_b32_e32 v10, 0xffff0000, v11
	v_add_f32_e32 v9, v9, v10
	v_lshlrev_b32_e32 v10, 16, v12
	v_add_f32_e32 v10, v2, v10
	v_and_b32_e32 v2, 0xffff0000, v12
	v_add_f32_e32 v11, v3, v2
	v_lshlrev_b32_e32 v2, 16, v13
	v_add_f32_e32 v12, v4, v2
	v_and_b32_e32 v2, 0xffff0000, v13
	v_add_f32_e32 v6, v6, v15
	v_add_f32_e32 v13, v5, v2
	v_cvt_pk_bf16_f32 v2, v6, v7
	v_cvt_pk_bf16_f32 v3, v8, v9
	v_cvt_pk_bf16_f32 v4, v10, v11
	v_cvt_pk_bf16_f32 v5, v12, v13
	ds_write_b128 v210, v[2:5] offset:64
	v_mul_f32_e32 v2, v7, v7
	v_mul_f32_e32 v3, v9, v9
	v_fmac_f32_e32 v2, v6, v6
	v_fmac_f32_e32 v3, v8, v8
	v_add_f32_e32 v2, v2, v3
	v_mul_f32_e32 v3, v11, v11
	v_mul_f32_e32 v4, v13, v13
	v_fmac_f32_e32 v3, v10, v10
	v_fmac_f32_e32 v4, v12, v12
	v_add_f32_e32 v3, v3, v4
	v_add_f32_e32 v2, v2, v3
	v_add_f32_e32 v12, v14, v2
	ds_read_b128 v[2:5], v211
	v_lshl_add_u64 v[6:7], s[76:77], 0, v[90:91]
	v_lshl_add_u64 v[6:7], v[6:7], 0, s[46:47]
	v_lshl_add_u64 v[10:11], v[6:7], 0, v[0:1]
	ds_read_b128 v[6:9], v211 offset:1152
	s_waitcnt lgkmcnt(1)
	global_store_dwordx4 v[10:11], v[2:5], off nt
	s_nop 1
	v_lshl_add_u64 v[2:3], s[76:77], 0, v[96:97]
	v_lshl_add_u64 v[2:3], v[2:3], 0, s[46:47]
	v_lshl_add_u64 v[2:3], v[2:3], 0, v[0:1]
	s_waitcnt lgkmcnt(0)
	global_store_dwordx4 v[2:3], v[6:9], off nt
	v_mov_b32_e32 v2, v12
	s_nop 1
	v_permlane16_swap_b32_e32 v12, v2
	v_add_f32_e32 v2, v12, v2
	v_mov_b32_e32 v3, v2
	s_nop 1
	v_permlane32_swap_b32_e32 v2, v3
	v_add_f32_e32 v167, v2, v3
	v_mbcnt_lo_u32_b32 v200, -1, 0
	v_mbcnt_hi_u32_b32 v200, -1, v200
	v_lshrrev_b32_e32 v201, 4, v200
	v_cmp_eq_u32_e64 s[100:101], 1, v201
	s_nop 1
	v_cndmask_b32_e64 v212, v164, v165, s[100:101]
	v_cmp_eq_u32_e64 s[100:101], 2, v201
	s_nop 1
	v_cndmask_b32_e64 v212, v212, v166, s[100:101]
	v_cmp_eq_u32_e64 s[100:101], 3, v201
	s_nop 1
	v_cndmask_b32_e64 v212, v212, v167, s[100:101]
	s_nop 1
	s_add_u32 s100, s82, s44
	s_addc_u32 s101, s83, s45
	v_or_b32_e32 v201, s42, v174
	v_lshlrev_b32_e32 v201, 2, v201
	v_and_b32_e32 v200, 48, v200
	v_lshl_add_u32 v201, v200, 2, v201
	global_store_dword v201, v212, s[100:101] offset:512
	s_andn2_b64 vcc, exec, s[36:37]
	s_mov_b64 s[36:37], -1
	s_cbranch_vccnz .LBB0_915
	s_andn2_b64 vcc, exec, s[18:19]
	s_cbranch_vccnz .LBB0_914
	s_barrier
	s_branch .LBB0_914
